# residual-row (XB) epilogue stores write-back instead of write-through sc1, to keep rows in the producing XCD L2 for the next GEMM
# speedup vs baseline: 1.0103x; 1.0003x over previous
; __device__ __forceinline__ unsigned cvt_pk_bf16(float lo, float hi) { unsigned r; asm volatile("v_cvt_pk_bf16_f32 %0, %1, %2" : "=v"(r) : "v"(lo), "v"(hi)); return r; }
;     __device__ __forceinline__ void operator()(const f32x4 (&acc)[2][2][4][2], const Unit& u, int wr, int wc, int fr, int fq, PG8_LAS float* xt) const {
;     ...
;             for (int m = 0; m < 4; ++m) { const int row = row0 + ai * HALF + m * 16; const size_t off = (size_t)row * 2048 + col0; float s = 0.f;
; #pragma unroll
;                 for (int bj = 0; bj < 2; ++bj) { const size_t o2 = off + bj * HALF;
;                     f32x4 x0 = acc[ai][bj][m][0] * f, x1 = acc[ai][bj][m][1] * f;
;                     if (out_f32) { *(f32x4*)(xout + o2) = x0; *(f32x4*)(xout + o2 + 4) = x1; }
;                     else { u32x4 w; w.x = cvt_pk_bf16(x0[0], x0[1]); w.y = cvt_pk_bf16(x0[2], x0[3]); w.z = cvt_pk_bf16(x1[0], x1[1]); w.w = cvt_pk_bf16(x1[2], x1[3]);
;                         asm volatile("global_store_dwordx4 %0, %1, off sc1\n\ts_nop 1" :: "v"(xb + o2), "v"(w) : "memory");
;                         x0 = (f32x4){__uint_as_float(w.x << 16), __uint_as_float(w.x & 0xffff0000u), __uint_as_float(w.y << 16), __uint_as_float(w.y & 0xffff0000u)};
;                         x1 = (f32x4){__uint_as_float(w.z << 16), __uint_as_float(w.z & 0xffff0000u), __uint_as_float(w.w << 16), __uint_as_float(w.w & 0xffff0000u)}; }
;                     s += (x0[0] * x0[0] + x0[1] * x0[1]) + (x0[2] * x0[2] + x0[3] * x0[3]) + (x1[0] * x1[0] + x1[1] * x1[1]) + (x1[2] * x1[2] + x1[3] * x1[3]); }
;                 s += __shfl_xor(s, 16); s += __shfl_xor(s, 32);
;                 if (fq == 0) xt[(ai * HALF + wr * 64 + m * 16 + fr) * 4 + wc] = s; }
.LBB0_312:
	s_lshl_b32 s17, s55, 8
	v_add_u32_e32 v142, s17, v147
	v_ashrrev_i32_e32 v143, 31, v142
	v_pk_mul_f32 v[144:145], v[2:3], 0.5 op_sel_hi:[1,0]
	v_pk_mul_f32 v[154:155], v[0:1], 0.5 op_sel_hi:[1,0]
	v_lshl_add_u32 v140, s16, 8, v146
	v_cvt_pk_bf16_f32 v154, v154, v155
	v_cvt_pk_bf16_f32 v155, v144, v145
	v_lshlrev_b64 v[144:145], 12, v[142:143]
	v_ashrrev_i32_e32 v141, 31, v140
	v_pk_mul_f32 v[156:157], v[4:5], 0.5 op_sel_hi:[1,0]
	v_lshl_add_u64 v[144:145], s[2:3], 0, v[144:145]
	v_pk_mul_f32 v[158:159], v[6:7], 0.5 op_sel_hi:[1,0]
	v_cvt_pk_bf16_f32 v156, v156, v157
	v_lshl_add_u64 v[144:145], v[140:141], 1, v[144:145]
	v_cvt_pk_bf16_f32 v157, v158, v159
	v_lshlrev_b32_e32 v153, 16, v154
	global_store_dwordx4 v[144:145], v[154:157], off
	s_nop 1
	v_and_b32_e32 v154, 0xffff0000, v154
	v_lshlrev_b32_e32 v158, 16, v155
	v_and_b32_e32 v155, 0xffff0000, v155
	v_mul_f32_e32 v154, v154, v154
	v_fmac_f32_e32 v154, v153, v153
	v_mul_f32_e32 v153, v155, v155
	v_lshlrev_b32_e32 v159, 16, v156
	v_and_b32_e32 v156, 0xffff0000, v156
	v_fmac_f32_e32 v153, v158, v158
	v_add_f32_e32 v153, v154, v153
	v_mul_f32_e32 v154, v156, v156
	v_lshlrev_b32_e32 v160, 16, v157
	v_and_b32_e32 v157, 0xffff0000, v157
	v_fmac_f32_e32 v154, v159, v159
	v_add_f32_e32 v153, v153, v154
	v_mul_f32_e32 v154, v157, v157
	v_fmac_f32_e32 v154, v160, v160
	v_add_f32_e32 v153, v154, v153
	v_pk_mul_f32 v[156:157], v[10:11], 0.5 op_sel_hi:[1,0]
	v_pk_mul_f32 v[154:155], v[8:9], 0.5 op_sel_hi:[1,0]
	v_lshl_add_u64 v[144:145], v[144:145], 0, s[24:25]
	v_pk_mul_f32 v[158:159], v[14:15], 0.5 op_sel_hi:[1,0]
	v_pk_mul_f32 v[160:161], v[12:13], 0.5 op_sel_hi:[1,0]
	v_cvt_pk_bf16_f32 v154, v154, v155
	v_cvt_pk_bf16_f32 v155, v156, v157
	s_nop 0
	v_cvt_pk_bf16_f32 v156, v160, v161
	v_cvt_pk_bf16_f32 v157, v158, v159
	s_nop 0
	global_store_dwordx4 v[144:145], v[154:157], off
	s_nop 1
	v_and_b32_e32 v145, 0xffff0000, v154
	v_lshlrev_b32_e32 v144, 16, v154
	v_lshlrev_b32_e32 v154, 16, v155
	v_and_b32_e32 v155, 0xffff0000, v155
	v_mul_f32_e32 v145, v145, v145
	v_fmac_f32_e32 v145, v144, v144
	v_mul_f32_e32 v144, v155, v155
	v_lshlrev_b32_e32 v158, 16, v156
	v_and_b32_e32 v156, 0xffff0000, v156
	v_fmac_f32_e32 v144, v154, v154
	v_add_f32_e32 v144, v145, v144
	v_mul_f32_e32 v145, v156, v156
	v_lshlrev_b32_e32 v159, 16, v157
	v_and_b32_e32 v157, 0xffff0000, v157
	v_fmac_f32_e32 v145, v158, v158
	v_add_f32_e32 v144, v144, v145
	v_mul_f32_e32 v145, v157, v157
	v_fmac_f32_e32 v145, v159, v159
	v_add_f32_e32 v144, v145, v144
	v_add_f32_e32 v144, v153, v144
	ds_bpermute_b32 v145, v218, v144
	s_waitcnt lgkmcnt(0)
	v_add_f32_e32 v144, v144, v145
	ds_bpermute_b32 v145, v219, v144
	s_and_saveexec_b64 s[40:41], s[0:1]
	s_cbranch_execz .LBB0_314
	s_waitcnt lgkmcnt(0)
	v_add_f32_e32 v144, v144, v145
	ds_write_b32 v152, v144
.LBB0_314:
	s_or_b64 exec, exec, s[40:41]
	v_or_b32_e32 v144, 16, v142
	s_waitcnt lgkmcnt(0)
	v_ashrrev_i32_e32 v145, 31, v144
	v_pk_mul_f32 v[154:155], v[16:17], 0.5 op_sel_hi:[1,0]
	v_lshlrev_b64 v[144:145], 12, v[144:145]
	v_pk_mul_f32 v[156:157], v[18:19], 0.5 op_sel_hi:[1,0]
	v_cvt_pk_bf16_f32 v154, v154, v155
	v_lshl_add_u64 v[144:145], s[2:3], 0, v[144:145]
	v_pk_mul_f32 v[158:159], v[22:23], 0.5 op_sel_hi:[1,0]
	v_pk_mul_f32 v[160:161], v[20:21], 0.5 op_sel_hi:[1,0]
	v_cvt_pk_bf16_f32 v155, v156, v157
	v_lshl_add_u64 v[144:145], v[140:141], 1, v[144:145]
	v_cvt_pk_bf16_f32 v156, v160, v161
	v_cvt_pk_bf16_f32 v157, v158, v159
	v_lshlrev_b32_e32 v153, 16, v154
	global_store_dwordx4 v[144:145], v[154:157], off
	s_nop 1
	v_and_b32_e32 v154, 0xffff0000, v154
	v_lshlrev_b32_e32 v158, 16, v155
	v_and_b32_e32 v155, 0xffff0000, v155
	v_mul_f32_e32 v154, v154, v154
	v_fmac_f32_e32 v154, v153, v153
	v_mul_f32_e32 v153, v155, v155
	v_lshlrev_b32_e32 v159, 16, v156
	v_and_b32_e32 v156, 0xffff0000, v156
	v_fmac_f32_e32 v153, v158, v158
	v_add_f32_e32 v153, v154, v153
	v_mul_f32_e32 v154, v156, v156
	v_lshlrev_b32_e32 v160, 16, v157
	v_and_b32_e32 v157, 0xffff0000, v157
	v_fmac_f32_e32 v154, v159, v159
	v_add_f32_e32 v153, v153, v154
	v_mul_f32_e32 v154, v157, v157
	v_fmac_f32_e32 v154, v160, v160
	v_add_f32_e32 v153, v154, v153
	v_pk_mul_f32 v[156:157], v[26:27], 0.5 op_sel_hi:[1,0]
	v_pk_mul_f32 v[154:155], v[24:25], 0.5 op_sel_hi:[1,0]
	v_lshl_add_u64 v[144:145], v[144:145], 0, s[24:25]
	v_pk_mul_f32 v[158:159], v[30:31], 0.5 op_sel_hi:[1,0]
	v_pk_mul_f32 v[160:161], v[28:29], 0.5 op_sel_hi:[1,0]
	v_cvt_pk_bf16_f32 v154, v154, v155
	v_cvt_pk_bf16_f32 v155, v156, v157
	s_nop 0
	v_cvt_pk_bf16_f32 v156, v160, v161
	v_cvt_pk_bf16_f32 v157, v158, v159
	s_nop 0
	global_store_dwordx4 v[144:145], v[154:157], off
	s_nop 1
	v_and_b32_e32 v145, 0xffff0000, v154
	v_lshlrev_b32_e32 v144, 16, v154
	v_lshlrev_b32_e32 v154, 16, v155
	v_and_b32_e32 v155, 0xffff0000, v155
	v_mul_f32_e32 v145, v145, v145
	v_fmac_f32_e32 v145, v144, v144
	v_mul_f32_e32 v144, v155, v155
	v_lshlrev_b32_e32 v158, 16, v156
	v_and_b32_e32 v156, 0xffff0000, v156
	v_fmac_f32_e32 v144, v154, v154
	v_add_f32_e32 v144, v145, v144
	v_mul_f32_e32 v145, v156, v156
	v_lshlrev_b32_e32 v159, 16, v157
	v_and_b32_e32 v157, 0xffff0000, v157
	v_fmac_f32_e32 v145, v158, v158
	v_add_f32_e32 v144, v144, v145
	v_mul_f32_e32 v145, v157, v157
	v_fmac_f32_e32 v145, v159, v159
	v_add_f32_e32 v144, v145, v144
	v_add_f32_e32 v144, v153, v144
	ds_bpermute_b32 v145, v218, v144
	s_waitcnt lgkmcnt(0)
	v_add_f32_e32 v144, v144, v145
	ds_bpermute_b32 v145, v219, v144
	s_and_saveexec_b64 s[40:41], s[0:1]
	s_cbranch_execz .LBB0_316
	s_waitcnt lgkmcnt(0)
	v_add_f32_e32 v144, v144, v145
	ds_write_b32 v152, v144 offset:256
; __device__ __forceinline__ unsigned cvt_pk_bf16(float lo, float hi) { unsigned r; asm volatile("v_cvt_pk_bf16_f32 %0, %1, %2" : "=v"(r) : "v"(lo), "v"(hi)); return r; }
;     __device__ __forceinline__ void operator()(const f32x4 (&acc)[2][2][4][2], const Unit& u, int wr, int wc, int fr, int fq, PG8_LAS float* xt) const {
;     ...
;             for (int m = 0; m < 4; ++m) { const int row = row0 + ai * HALF + m * 16; const size_t off = (size_t)row * 2048 + col0; float s = 0.f;
; #pragma unroll
;                 for (int bj = 0; bj < 2; ++bj) { const size_t o2 = off + bj * HALF;
;                     f32x4 x0 = acc[ai][bj][m][0] * f, x1 = acc[ai][bj][m][1] * f;
;                     if (out_f32) { *(f32x4*)(xout + o2) = x0; *(f32x4*)(xout + o2 + 4) = x1; }
;                     else { u32x4 w; w.x = cvt_pk_bf16(x0[0], x0[1]); w.y = cvt_pk_bf16(x0[2], x0[3]); w.z = cvt_pk_bf16(x1[0], x1[1]); w.w = cvt_pk_bf16(x1[2], x1[3]);
;                         asm volatile("global_store_dwordx4 %0, %1, off sc1\n\ts_nop 1" :: "v"(xb + o2), "v"(w) : "memory");
;                         x0 = (f32x4){__uint_as_float(w.x << 16), __uint_as_float(w.x & 0xffff0000u), __uint_as_float(w.y << 16), __uint_as_float(w.y & 0xffff0000u)};
;                         x1 = (f32x4){__uint_as_float(w.z << 16), __uint_as_float(w.z & 0xffff0000u), __uint_as_float(w.w << 16), __uint_as_float(w.w & 0xffff0000u)}; }
;                     s += (x0[0] * x0[0] + x0[1] * x0[1]) + (x0[2] * x0[2] + x0[3] * x0[3]) + (x1[0] * x1[0] + x1[1] * x1[1]) + (x1[2] * x1[2] + x1[3] * x1[3]); }
;                 s += __shfl_xor(s, 16); s += __shfl_xor(s, 32);
;                 if (fq == 0) xt[(ai * HALF + wr * 64 + m * 16 + fr) * 4 + wc] = s; }
.LBB0_316:
	s_or_b64 exec, exec, s[40:41]
	v_or_b32_e32 v144, 32, v142
	s_waitcnt lgkmcnt(0)
	v_ashrrev_i32_e32 v145, 31, v144
	v_pk_mul_f32 v[154:155], v[32:33], 0.5 op_sel_hi:[1,0]
	v_lshlrev_b64 v[144:145], 12, v[144:145]
	v_pk_mul_f32 v[156:157], v[34:35], 0.5 op_sel_hi:[1,0]
	v_cvt_pk_bf16_f32 v154, v154, v155
	v_lshl_add_u64 v[144:145], s[2:3], 0, v[144:145]
	v_pk_mul_f32 v[158:159], v[38:39], 0.5 op_sel_hi:[1,0]
	v_pk_mul_f32 v[160:161], v[36:37], 0.5 op_sel_hi:[1,0]
	v_cvt_pk_bf16_f32 v155, v156, v157
	v_lshl_add_u64 v[144:145], v[140:141], 1, v[144:145]
	v_cvt_pk_bf16_f32 v156, v160, v161
	v_cvt_pk_bf16_f32 v157, v158, v159
	v_lshlrev_b32_e32 v153, 16, v154
	global_store_dwordx4 v[144:145], v[154:157], off
	s_nop 1
	v_and_b32_e32 v154, 0xffff0000, v154
	v_lshlrev_b32_e32 v158, 16, v155
	v_and_b32_e32 v155, 0xffff0000, v155
	v_mul_f32_e32 v154, v154, v154
	v_fmac_f32_e32 v154, v153, v153
	v_mul_f32_e32 v153, v155, v155
	v_lshlrev_b32_e32 v159, 16, v156
	v_and_b32_e32 v156, 0xffff0000, v156
	v_fmac_f32_e32 v153, v158, v158
	v_add_f32_e32 v153, v154, v153
	v_mul_f32_e32 v154, v156, v156
	v_lshlrev_b32_e32 v160, 16, v157
	v_and_b32_e32 v157, 0xffff0000, v157
	v_fmac_f32_e32 v154, v159, v159
	v_add_f32_e32 v153, v153, v154
	v_mul_f32_e32 v154, v157, v157
	v_fmac_f32_e32 v154, v160, v160
	v_add_f32_e32 v153, v154, v153
	v_pk_mul_f32 v[156:157], v[42:43], 0.5 op_sel_hi:[1,0]
	v_pk_mul_f32 v[154:155], v[40:41], 0.5 op_sel_hi:[1,0]
	v_lshl_add_u64 v[144:145], v[144:145], 0, s[24:25]
	v_pk_mul_f32 v[158:159], v[46:47], 0.5 op_sel_hi:[1,0]
	v_pk_mul_f32 v[160:161], v[44:45], 0.5 op_sel_hi:[1,0]
	v_cvt_pk_bf16_f32 v154, v154, v155
	v_cvt_pk_bf16_f32 v155, v156, v157
	s_nop 0
	v_cvt_pk_bf16_f32 v156, v160, v161
	v_cvt_pk_bf16_f32 v157, v158, v159
	s_nop 0
	global_store_dwordx4 v[144:145], v[154:157], off
	s_nop 1
	v_and_b32_e32 v145, 0xffff0000, v154
	v_lshlrev_b32_e32 v144, 16, v154
	v_lshlrev_b32_e32 v154, 16, v155
	v_and_b32_e32 v155, 0xffff0000, v155
	v_mul_f32_e32 v145, v145, v145
	v_fmac_f32_e32 v145, v144, v144
	v_mul_f32_e32 v144, v155, v155
	v_lshlrev_b32_e32 v158, 16, v156
	v_and_b32_e32 v156, 0xffff0000, v156
	v_fmac_f32_e32 v144, v154, v154
	v_add_f32_e32 v144, v145, v144
	v_mul_f32_e32 v145, v156, v156
	v_lshlrev_b32_e32 v159, 16, v157
	v_and_b32_e32 v157, 0xffff0000, v157
	v_fmac_f32_e32 v145, v158, v158
	v_add_f32_e32 v144, v144, v145
	v_mul_f32_e32 v145, v157, v157
	v_fmac_f32_e32 v145, v159, v159
	v_add_f32_e32 v144, v145, v144
	v_add_f32_e32 v144, v153, v144
	ds_bpermute_b32 v145, v218, v144
	s_waitcnt lgkmcnt(0)
	v_add_f32_e32 v144, v144, v145
	ds_bpermute_b32 v145, v219, v144
	s_and_saveexec_b64 s[40:41], s[0:1]
	s_cbranch_execz .LBB0_318
	s_waitcnt lgkmcnt(0)
	v_add_f32_e32 v144, v144, v145
	ds_write_b32 v152, v144 offset:512
.LBB0_318:
	s_or_b64 exec, exec, s[40:41]
	v_or_b32_e32 v144, 48, v142
	s_waitcnt lgkmcnt(0)
	v_ashrrev_i32_e32 v145, 31, v144
	v_pk_mul_f32 v[154:155], v[48:49], 0.5 op_sel_hi:[1,0]
	v_lshlrev_b64 v[144:145], 12, v[144:145]
	v_pk_mul_f32 v[156:157], v[50:51], 0.5 op_sel_hi:[1,0]
	v_cvt_pk_bf16_f32 v154, v154, v155
	v_lshl_add_u64 v[144:145], s[2:3], 0, v[144:145]
	v_pk_mul_f32 v[158:159], v[54:55], 0.5 op_sel_hi:[1,0]
	v_pk_mul_f32 v[160:161], v[52:53], 0.5 op_sel_hi:[1,0]
	v_cvt_pk_bf16_f32 v155, v156, v157
	v_lshl_add_u64 v[144:145], v[140:141], 1, v[144:145]
	v_cvt_pk_bf16_f32 v156, v160, v161
	v_cvt_pk_bf16_f32 v157, v158, v159
	v_lshlrev_b32_e32 v153, 16, v154
	global_store_dwordx4 v[144:145], v[154:157], off
	s_nop 1
	v_and_b32_e32 v154, 0xffff0000, v154
	v_lshlrev_b32_e32 v158, 16, v155
	v_and_b32_e32 v155, 0xffff0000, v155
	v_mul_f32_e32 v154, v154, v154
	v_fmac_f32_e32 v154, v153, v153
	v_mul_f32_e32 v153, v155, v155
	v_lshlrev_b32_e32 v159, 16, v156
	v_and_b32_e32 v156, 0xffff0000, v156
	v_fmac_f32_e32 v153, v158, v158
	v_add_f32_e32 v153, v154, v153
	v_mul_f32_e32 v154, v156, v156
	v_lshlrev_b32_e32 v160, 16, v157
	v_and_b32_e32 v157, 0xffff0000, v157
	v_fmac_f32_e32 v154, v159, v159
	v_add_f32_e32 v153, v153, v154
	v_mul_f32_e32 v154, v157, v157
	v_fmac_f32_e32 v154, v160, v160
	v_add_f32_e32 v153, v154, v153
	v_pk_mul_f32 v[156:157], v[58:59], 0.5 op_sel_hi:[1,0]
	v_pk_mul_f32 v[154:155], v[56:57], 0.5 op_sel_hi:[1,0]
	v_lshl_add_u64 v[144:145], v[144:145], 0, s[24:25]
	v_pk_mul_f32 v[158:159], v[62:63], 0.5 op_sel_hi:[1,0]
	v_pk_mul_f32 v[160:161], v[60:61], 0.5 op_sel_hi:[1,0]
	v_cvt_pk_bf16_f32 v154, v154, v155
	v_cvt_pk_bf16_f32 v155, v156, v157
	s_nop 0
	v_cvt_pk_bf16_f32 v156, v160, v161
	v_cvt_pk_bf16_f32 v157, v158, v159
	s_nop 0
	global_store_dwordx4 v[144:145], v[154:157], off
	s_nop 1
	v_and_b32_e32 v145, 0xffff0000, v154
	v_lshlrev_b32_e32 v144, 16, v154
	v_lshlrev_b32_e32 v154, 16, v155
	v_and_b32_e32 v155, 0xffff0000, v155
	v_mul_f32_e32 v145, v145, v145
	v_fmac_f32_e32 v145, v144, v144
	v_mul_f32_e32 v144, v155, v155
	v_lshlrev_b32_e32 v158, 16, v156
	v_and_b32_e32 v156, 0xffff0000, v156
	v_fmac_f32_e32 v144, v154, v154
	v_add_f32_e32 v144, v145, v144
	v_mul_f32_e32 v145, v156, v156
	v_lshlrev_b32_e32 v159, 16, v157
	v_and_b32_e32 v157, 0xffff0000, v157
	v_fmac_f32_e32 v145, v158, v158
	v_add_f32_e32 v144, v144, v145
	v_mul_f32_e32 v145, v157, v157
	v_fmac_f32_e32 v145, v159, v159
	v_add_f32_e32 v144, v145, v144
	v_add_f32_e32 v144, v153, v144
	ds_bpermute_b32 v145, v218, v144
	s_waitcnt lgkmcnt(0)
	v_add_f32_e32 v144, v144, v145
	ds_bpermute_b32 v145, v219, v144
	s_and_saveexec_b64 s[40:41], s[0:1]
	s_cbranch_execz .LBB0_320
	s_waitcnt lgkmcnt(0)
	v_add_f32_e32 v144, v144, v145
	ds_write_b32 v152, v144 offset:768
; __device__ __forceinline__ unsigned cvt_pk_bf16(float lo, float hi) { unsigned r; asm volatile("v_cvt_pk_bf16_f32 %0, %1, %2" : "=v"(r) : "v"(lo), "v"(hi)); return r; }
;     __device__ __forceinline__ void operator()(const f32x4 (&acc)[2][2][4][2], const Unit& u, int wr, int wc, int fr, int fq, PG8_LAS float* xt) const {
;     ...
;             for (int m = 0; m < 4; ++m) { const int row = row0 + ai * HALF + m * 16; const size_t off = (size_t)row * 2048 + col0; float s = 0.f;
; #pragma unroll
;                 for (int bj = 0; bj < 2; ++bj) { const size_t o2 = off + bj * HALF;
;                     f32x4 x0 = acc[ai][bj][m][0] * f, x1 = acc[ai][bj][m][1] * f;
;                     if (out_f32) { *(f32x4*)(xout + o2) = x0; *(f32x4*)(xout + o2 + 4) = x1; }
;                     else { u32x4 w; w.x = cvt_pk_bf16(x0[0], x0[1]); w.y = cvt_pk_bf16(x0[2], x0[3]); w.z = cvt_pk_bf16(x1[0], x1[1]); w.w = cvt_pk_bf16(x1[2], x1[3]);
;                         asm volatile("global_store_dwordx4 %0, %1, off sc1\n\ts_nop 1" :: "v"(xb + o2), "v"(w) : "memory");
;                         x0 = (f32x4){__uint_as_float(w.x << 16), __uint_as_float(w.x & 0xffff0000u), __uint_as_float(w.y << 16), __uint_as_float(w.y & 0xffff0000u)};
;                         x1 = (f32x4){__uint_as_float(w.z << 16), __uint_as_float(w.z & 0xffff0000u), __uint_as_float(w.w << 16), __uint_as_float(w.w & 0xffff0000u)}; }
;                     s += (x0[0] * x0[0] + x0[1] * x0[1]) + (x0[2] * x0[2] + x0[3] * x0[3]) + (x1[0] * x1[0] + x1[1] * x1[1]) + (x1[2] * x1[2] + x1[3] * x1[3]); }
;                 s += __shfl_xor(s, 16); s += __shfl_xor(s, 32);
;                 if (fq == 0) xt[(ai * HALF + wr * 64 + m * 16 + fr) * 4 + wc] = s; }
.LBB0_320:
	s_or_b64 exec, exec, s[40:41]
	s_waitcnt lgkmcnt(0)
	v_lshlrev_b64 v[144:145], 12, v[142:143]
	v_pk_mul_f32 v[154:155], v[64:65], 0.5 op_sel_hi:[1,0]
	v_lshl_add_u64 v[144:145], s[2:3], 0, v[144:145]
	v_pk_mul_f32 v[156:157], v[66:67], 0.5 op_sel_hi:[1,0]
	v_pk_mul_f32 v[158:159], v[70:71], 0.5 op_sel_hi:[1,0]
	v_cvt_pk_bf16_f32 v154, v154, v155
	v_lshl_add_u64 v[144:145], v[140:141], 1, v[144:145]
	v_pk_mul_f32 v[160:161], v[68:69], 0.5 op_sel_hi:[1,0]
	v_cvt_pk_bf16_f32 v155, v156, v157
	v_lshlrev_b32_e32 v153, 16, v154
	v_cvt_pk_bf16_f32 v156, v160, v161
	v_cvt_pk_bf16_f32 v157, v158, v159
	v_lshl_add_u64 v[158:159], v[144:145], 0, s[74:75]
	global_store_dwordx4 v[158:159], v[154:157], off
	s_nop 1
	v_and_b32_e32 v154, 0xffff0000, v154
	v_lshlrev_b32_e32 v158, 16, v155
	v_and_b32_e32 v155, 0xffff0000, v155
	v_mul_f32_e32 v154, v154, v154
	v_fmac_f32_e32 v154, v153, v153
	v_mul_f32_e32 v153, v155, v155
	v_lshlrev_b32_e32 v159, 16, v156
	v_and_b32_e32 v156, 0xffff0000, v156
	v_fmac_f32_e32 v153, v158, v158
	v_add_f32_e32 v153, v154, v153
	v_mul_f32_e32 v154, v156, v156
	v_lshlrev_b32_e32 v160, 16, v157
	v_and_b32_e32 v157, 0xffff0000, v157
	v_fmac_f32_e32 v154, v159, v159
	v_add_f32_e32 v153, v153, v154
	v_mul_f32_e32 v154, v157, v157
	v_fmac_f32_e32 v154, v160, v160
	v_add_f32_e32 v153, v154, v153
	v_pk_mul_f32 v[156:157], v[74:75], 0.5 op_sel_hi:[1,0]
	v_pk_mul_f32 v[154:155], v[72:73], 0.5 op_sel_hi:[1,0]
	v_pk_mul_f32 v[158:159], v[78:79], 0.5 op_sel_hi:[1,0]
	s_mov_b64 s[40:41], 0x80100
	v_pk_mul_f32 v[160:161], v[76:77], 0.5 op_sel_hi:[1,0]
	v_cvt_pk_bf16_f32 v154, v154, v155
	v_cvt_pk_bf16_f32 v155, v156, v157
	s_nop 0
	v_cvt_pk_bf16_f32 v156, v160, v161
	v_cvt_pk_bf16_f32 v157, v158, v159
	v_lshl_add_u64 v[158:159], v[144:145], 0, s[40:41]
	global_store_dwordx4 v[158:159], v[154:157], off
	s_nop 1
	v_lshlrev_b32_e32 v158, 16, v154
	v_and_b32_e32 v154, 0xffff0000, v154
	v_lshlrev_b32_e32 v159, 16, v155
	v_and_b32_e32 v155, 0xffff0000, v155
	v_mul_f32_e32 v154, v154, v154
	v_mul_f32_e32 v155, v155, v155
	v_lshlrev_b32_e32 v160, 16, v156
	v_and_b32_e32 v156, 0xffff0000, v156
	v_fmac_f32_e32 v154, v158, v158
	v_fmac_f32_e32 v155, v159, v159
	v_add_f32_e32 v154, v154, v155
	v_mul_f32_e32 v155, v156, v156
	v_lshlrev_b32_e32 v161, 16, v157
	v_and_b32_e32 v157, 0xffff0000, v157
	v_fmac_f32_e32 v155, v160, v160
	v_add_f32_e32 v154, v154, v155
	v_mul_f32_e32 v155, v157, v157
	v_fmac_f32_e32 v155, v161, v161
	v_add_f32_e32 v154, v155, v154
	v_add_f32_e32 v153, v153, v154
	ds_bpermute_b32 v154, v218, v153
	s_waitcnt lgkmcnt(0)
	v_add_f32_e32 v153, v153, v154
	ds_bpermute_b32 v154, v219, v153
	s_and_saveexec_b64 s[40:41], s[0:1]
	s_cbranch_execz .LBB0_322
	s_waitcnt lgkmcnt(0)
	v_add_f32_e32 v153, v153, v154
	ds_write_b32 v152, v153 offset:2048
.LBB0_322:
	s_or_b64 exec, exec, s[40:41]
	s_waitcnt lgkmcnt(0)
	v_pk_mul_f32 v[154:155], v[80:81], 0.5 op_sel_hi:[1,0]
	v_pk_mul_f32 v[156:157], v[82:83], 0.5 op_sel_hi:[1,0]
	v_pk_mul_f32 v[158:159], v[86:87], 0.5 op_sel_hi:[1,0]
	v_cvt_pk_bf16_f32 v154, v154, v155
	s_mov_b64 s[40:41], 0x90000
	v_pk_mul_f32 v[160:161], v[84:85], 0.5 op_sel_hi:[1,0]
	v_cvt_pk_bf16_f32 v155, v156, v157
	v_lshlrev_b32_e32 v153, 16, v154
	v_cvt_pk_bf16_f32 v156, v160, v161
	v_cvt_pk_bf16_f32 v157, v158, v159
	v_lshl_add_u64 v[158:159], v[144:145], 0, s[40:41]
	global_store_dwordx4 v[158:159], v[154:157], off
	s_nop 1
	v_and_b32_e32 v154, 0xffff0000, v154
	v_lshlrev_b32_e32 v158, 16, v155
	v_and_b32_e32 v155, 0xffff0000, v155
	v_mul_f32_e32 v154, v154, v154
	v_fmac_f32_e32 v154, v153, v153
	v_mul_f32_e32 v153, v155, v155
	v_lshlrev_b32_e32 v159, 16, v156
	v_and_b32_e32 v156, 0xffff0000, v156
	v_fmac_f32_e32 v153, v158, v158
	v_add_f32_e32 v153, v154, v153
	v_mul_f32_e32 v154, v156, v156
	v_lshlrev_b32_e32 v160, 16, v157
	v_and_b32_e32 v157, 0xffff0000, v157
	v_fmac_f32_e32 v154, v159, v159
	v_add_f32_e32 v153, v153, v154
	v_mul_f32_e32 v154, v157, v157
	v_fmac_f32_e32 v154, v160, v160
	s_mov_b64 s[40:41], 0x90100
	v_add_f32_e32 v153, v154, v153
	v_pk_mul_f32 v[156:157], v[90:91], 0.5 op_sel_hi:[1,0]
	v_pk_mul_f32 v[154:155], v[88:89], 0.5 op_sel_hi:[1,0]
	v_lshl_add_u64 v[144:145], v[144:145], 0, s[40:41]
	v_pk_mul_f32 v[158:159], v[94:95], 0.5 op_sel_hi:[1,0]
	v_pk_mul_f32 v[160:161], v[92:93], 0.5 op_sel_hi:[1,0]
	v_cvt_pk_bf16_f32 v154, v154, v155
	v_cvt_pk_bf16_f32 v155, v156, v157
	s_nop 0
	v_cvt_pk_bf16_f32 v156, v160, v161
	v_cvt_pk_bf16_f32 v157, v158, v159
	s_nop 0
	global_store_dwordx4 v[144:145], v[154:157], off
	s_nop 1
	v_and_b32_e32 v145, 0xffff0000, v154
	v_lshlrev_b32_e32 v144, 16, v154
	v_lshlrev_b32_e32 v154, 16, v155
	v_and_b32_e32 v155, 0xffff0000, v155
	v_mul_f32_e32 v145, v145, v145
	v_fmac_f32_e32 v145, v144, v144
	v_mul_f32_e32 v144, v155, v155
	v_lshlrev_b32_e32 v158, 16, v156
	v_and_b32_e32 v156, 0xffff0000, v156
	v_fmac_f32_e32 v144, v154, v154
	v_add_f32_e32 v144, v145, v144
	v_mul_f32_e32 v145, v156, v156
	v_lshlrev_b32_e32 v159, 16, v157
	v_and_b32_e32 v157, 0xffff0000, v157
	v_fmac_f32_e32 v145, v158, v158
	v_add_f32_e32 v144, v144, v145
	v_mul_f32_e32 v145, v157, v157
	v_fmac_f32_e32 v145, v159, v159
	v_add_f32_e32 v144, v145, v144
	v_add_f32_e32 v144, v153, v144
	ds_bpermute_b32 v145, v218, v144
	s_waitcnt lgkmcnt(0)
	v_add_f32_e32 v144, v144, v145
	ds_bpermute_b32 v145, v219, v144
	s_and_saveexec_b64 s[40:41], s[0:1]
	s_cbranch_execz .LBB0_324
	s_waitcnt lgkmcnt(0)
	v_add_f32_e32 v144, v144, v145
	ds_write_b32 v152, v144 offset:2304
; __device__ __forceinline__ unsigned cvt_pk_bf16(float lo, float hi) { unsigned r; asm volatile("v_cvt_pk_bf16_f32 %0, %1, %2" : "=v"(r) : "v"(lo), "v"(hi)); return r; }
;     __device__ __forceinline__ void operator()(const f32x4 (&acc)[2][2][4][2], const Unit& u, int wr, int wc, int fr, int fq, PG8_LAS float* xt) const {
;     ...
;             for (int m = 0; m < 4; ++m) { const int row = row0 + ai * HALF + m * 16; const size_t off = (size_t)row * 2048 + col0; float s = 0.f;
; #pragma unroll
;                 for (int bj = 0; bj < 2; ++bj) { const size_t o2 = off + bj * HALF;
;                     f32x4 x0 = acc[ai][bj][m][0] * f, x1 = acc[ai][bj][m][1] * f;
;                     if (out_f32) { *(f32x4*)(xout + o2) = x0; *(f32x4*)(xout + o2 + 4) = x1; }
;                     else { u32x4 w; w.x = cvt_pk_bf16(x0[0], x0[1]); w.y = cvt_pk_bf16(x0[2], x0[3]); w.z = cvt_pk_bf16(x1[0], x1[1]); w.w = cvt_pk_bf16(x1[2], x1[3]);
;                         asm volatile("global_store_dwordx4 %0, %1, off sc1\n\ts_nop 1" :: "v"(xb + o2), "v"(w) : "memory");
;                         x0 = (f32x4){__uint_as_float(w.x << 16), __uint_as_float(w.x & 0xffff0000u), __uint_as_float(w.y << 16), __uint_as_float(w.y & 0xffff0000u)};
;                         x1 = (f32x4){__uint_as_float(w.z << 16), __uint_as_float(w.z & 0xffff0000u), __uint_as_float(w.w << 16), __uint_as_float(w.w & 0xffff0000u)}; }
;                     s += (x0[0] * x0[0] + x0[1] * x0[1]) + (x0[2] * x0[2] + x0[3] * x0[3]) + (x1[0] * x1[0] + x1[1] * x1[1]) + (x1[2] * x1[2] + x1[3] * x1[3]); }
;                 s += __shfl_xor(s, 16); s += __shfl_xor(s, 32);
;                 if (fq == 0) xt[(ai * HALF + wr * 64 + m * 16 + fr) * 4 + wc] = s; }
.LBB0_324:
	s_or_b64 exec, exec, s[40:41]
	v_lshlrev_b64 v[154:155], 12, v[142:143]
	v_lshl_add_u64 v[154:155], s[2:3], 0, v[154:155]
	v_pk_mul_f32 v[142:143], v[98:99], 0.5 op_sel_hi:[1,0]
	v_lshl_add_u64 v[140:141], v[140:141], 1, v[154:155]
	s_mov_b64 s[40:41], 0xa0000
	s_waitcnt lgkmcnt(0)
	v_pk_mul_f32 v[144:145], v[100:101], 0.5 op_sel_hi:[1,0]
	v_cvt_pk_bf16_f32 v142, v142, v143
	v_lshl_add_u64 v[154:155], v[140:141], 0, s[40:41]
	v_cvt_pk_bf16_f32 v143, v144, v145
	v_pk_mul_f32 v[156:157], v[104:105], 0.5 op_sel_hi:[1,0]
	v_pk_mul_f32 v[158:159], v[102:103], 0.5 op_sel_hi:[1,0]
	v_lshlrev_b32_e32 v153, 16, v142
	v_cvt_pk_bf16_f32 v144, v158, v159
	v_cvt_pk_bf16_f32 v145, v156, v157
	s_mov_b64 s[40:41], 0xa0100
	global_store_dwordx4 v[154:155], v[142:145], off
	s_nop 1
	v_and_b32_e32 v142, 0xffff0000, v142
	v_lshlrev_b32_e32 v154, 16, v143
	v_and_b32_e32 v143, 0xffff0000, v143
	v_mul_f32_e32 v142, v142, v142
	v_mul_f32_e32 v143, v143, v143
	v_lshlrev_b32_e32 v155, 16, v144
	v_and_b32_e32 v144, 0xffff0000, v144
	v_fmac_f32_e32 v142, v153, v153
	v_fmac_f32_e32 v143, v154, v154
	v_add_f32_e32 v142, v142, v143
	v_mul_f32_e32 v143, v144, v144
	v_lshlrev_b32_e32 v156, 16, v145
	v_and_b32_e32 v145, 0xffff0000, v145
	v_fmac_f32_e32 v143, v155, v155
	v_add_f32_e32 v142, v142, v143
	v_mul_f32_e32 v143, v145, v145
	v_fmac_f32_e32 v143, v156, v156
	v_add_f32_e32 v153, v143, v142
	v_pk_mul_f32 v[144:145], v[108:109], 0.5 op_sel_hi:[1,0]
	v_pk_mul_f32 v[142:143], v[106:107], 0.5 op_sel_hi:[1,0]
	v_pk_mul_f32 v[154:155], v[112:113], 0.5 op_sel_hi:[1,0]
	v_pk_mul_f32 v[156:157], v[110:111], 0.5 op_sel_hi:[1,0]
	v_cvt_pk_bf16_f32 v142, v142, v143
	v_cvt_pk_bf16_f32 v143, v144, v145
	s_nop 0
	v_cvt_pk_bf16_f32 v144, v156, v157
	v_cvt_pk_bf16_f32 v145, v154, v155
	v_lshl_add_u64 v[154:155], v[140:141], 0, s[40:41]
	global_store_dwordx4 v[154:155], v[142:145], off
	s_nop 1
	v_lshlrev_b32_e32 v154, 16, v142
	v_and_b32_e32 v142, 0xffff0000, v142
	v_lshlrev_b32_e32 v155, 16, v143
	v_and_b32_e32 v143, 0xffff0000, v143
	v_mul_f32_e32 v142, v142, v142
	v_mul_f32_e32 v143, v143, v143
	v_lshlrev_b32_e32 v156, 16, v144
	v_and_b32_e32 v144, 0xffff0000, v144
	v_fmac_f32_e32 v142, v154, v154
	v_fmac_f32_e32 v143, v155, v155
	v_add_f32_e32 v142, v142, v143
	v_mul_f32_e32 v143, v144, v144
	v_lshlrev_b32_e32 v157, 16, v145
	v_and_b32_e32 v145, 0xffff0000, v145
	v_fmac_f32_e32 v143, v156, v156
	v_add_f32_e32 v142, v142, v143
	v_mul_f32_e32 v143, v145, v145
	v_fmac_f32_e32 v143, v157, v157
	v_add_f32_e32 v142, v143, v142
	v_add_f32_e32 v142, v153, v142
	ds_bpermute_b32 v143, v218, v142
	s_waitcnt lgkmcnt(0)
	v_add_f32_e32 v142, v142, v143
	ds_bpermute_b32 v143, v219, v142
	s_and_saveexec_b64 s[40:41], s[0:1]
	s_cbranch_execz .LBB0_326
	s_waitcnt lgkmcnt(0)
	v_add_f32_e32 v142, v142, v143
	ds_write_b32 v152, v142 offset:2560
.LBB0_326:
	s_or_b64 exec, exec, s[40:41]
	v_pk_mul_f32 v[144:145], v[116:117], 0.5 op_sel_hi:[1,0]
	s_waitcnt lgkmcnt(0)
	v_pk_mul_f32 v[142:143], v[114:115], 0.5 op_sel_hi:[1,0]
	v_pk_mul_f32 v[154:155], v[120:121], 0.5 op_sel_hi:[1,0]
	s_mov_b64 s[40:41], 0xb0000
	v_pk_mul_f32 v[156:157], v[118:119], 0.5 op_sel_hi:[1,0]
	v_cvt_pk_bf16_f32 v142, v142, v143
	v_cvt_pk_bf16_f32 v143, v144, v145
	s_nop 0
	v_cvt_pk_bf16_f32 v144, v156, v157
	v_cvt_pk_bf16_f32 v145, v154, v155
	v_lshl_add_u64 v[154:155], v[140:141], 0, s[40:41]
	global_store_dwordx4 v[154:155], v[142:145], off
	s_nop 1
	v_lshlrev_b32_e32 v153, 16, v142
	v_and_b32_e32 v142, 0xffff0000, v142
	v_lshlrev_b32_e32 v154, 16, v143
	v_and_b32_e32 v143, 0xffff0000, v143
	v_mul_f32_e32 v142, v142, v142
	v_mul_f32_e32 v143, v143, v143
	v_lshlrev_b32_e32 v155, 16, v144
	v_and_b32_e32 v144, 0xffff0000, v144
	v_fmac_f32_e32 v142, v153, v153
	v_fmac_f32_e32 v143, v154, v154
	v_add_f32_e32 v142, v142, v143
	v_mul_f32_e32 v143, v144, v144
	v_lshlrev_b32_e32 v156, 16, v145
	v_and_b32_e32 v145, 0xffff0000, v145
	v_fmac_f32_e32 v143, v155, v155
	v_add_f32_e32 v142, v142, v143
	v_mul_f32_e32 v143, v145, v145
	v_fmac_f32_e32 v143, v156, v156
	s_mov_b64 s[40:41], 0xb0100
	v_add_f32_e32 v153, v143, v142
	v_pk_mul_f32 v[144:145], v[124:125], 0.5 op_sel_hi:[1,0]
	v_pk_mul_f32 v[142:143], v[122:123], 0.5 op_sel_hi:[1,0]
	v_lshl_add_u64 v[140:141], v[140:141], 0, s[40:41]
	v_pk_mul_f32 v[154:155], v[128:129], 0.5 op_sel_hi:[1,0]
	v_pk_mul_f32 v[156:157], v[126:127], 0.5 op_sel_hi:[1,0]
	v_cvt_pk_bf16_f32 v142, v142, v143
	v_cvt_pk_bf16_f32 v143, v144, v145
	s_nop 0
	v_cvt_pk_bf16_f32 v144, v156, v157
	v_cvt_pk_bf16_f32 v145, v154, v155
	s_nop 0
	global_store_dwordx4 v[140:141], v[142:145], off
	s_nop 1
	v_and_b32_e32 v141, 0xffff0000, v142
	v_lshlrev_b32_e32 v140, 16, v142
	v_lshlrev_b32_e32 v142, 16, v143
	v_and_b32_e32 v143, 0xffff0000, v143
	v_mul_f32_e32 v141, v141, v141
	v_fmac_f32_e32 v141, v140, v140
	v_mul_f32_e32 v140, v143, v143
	v_lshlrev_b32_e32 v154, 16, v144
	v_and_b32_e32 v144, 0xffff0000, v144
	v_fmac_f32_e32 v140, v142, v142
	v_add_f32_e32 v140, v141, v140
	v_mul_f32_e32 v141, v144, v144
	v_lshlrev_b32_e32 v155, 16, v145
	v_and_b32_e32 v145, 0xffff0000, v145
	v_fmac_f32_e32 v141, v154, v154
	v_add_f32_e32 v140, v140, v141
	v_mul_f32_e32 v141, v145, v145
	v_fmac_f32_e32 v141, v155, v155
	v_add_f32_e32 v140, v141, v140
	v_add_f32_e32 v140, v153, v140
	ds_bpermute_b32 v141, v218, v140
	s_waitcnt lgkmcnt(0)
	v_add_f32_e32 v140, v140, v141
	ds_bpermute_b32 v141, v219, v140
	s_and_saveexec_b64 s[40:41], s[0:1]
	s_cbranch_execz .LBB0_328
	s_waitcnt lgkmcnt(0)
	v_add_f32_e32 v140, v140, v141
	ds_write_b32 v152, v140 offset:2816

; __device__ __forceinline__ unsigned cvt_pk_bf16(float lo, float hi) { unsigned r; asm volatile("v_cvt_pk_bf16_f32 %0, %1, %2" : "=v"(r) : "v"(lo), "v"(hi)); return r; }
;     __device__ __forceinline__ void operator()(const f32x4 (&acc)[2][2][4][2], const Unit& u, int wr, int wc, int fr, int fq, PG8_LAS float* xt) const {
;     ...
;             for (int m = 0; m < 4; ++m) { const int row = row0 + ai * HALF + m * 16; const size_t off = (size_t)row * 2048 + col0; float s = 0.f;
; #pragma unroll
;                 for (int bj = 0; bj < 2; ++bj) { const size_t o2 = off + bj * HALF;
;                     f32x4 x0 = acc[ai][bj][m][0] * f, x1 = acc[ai][bj][m][1] * f;
;                     if (out_f32) { *(f32x4*)(xout + o2) = x0; *(f32x4*)(xout + o2 + 4) = x1; }
;                     else { u32x4 w; w.x = cvt_pk_bf16(x0[0], x0[1]); w.y = cvt_pk_bf16(x0[2], x0[3]); w.z = cvt_pk_bf16(x1[0], x1[1]); w.w = cvt_pk_bf16(x1[2], x1[3]);
;                         asm volatile("global_store_dwordx4 %0, %1, off sc1\n\ts_nop 1" :: "v"(xb + o2), "v"(w) : "memory");
;                         x0 = (f32x4){__uint_as_float(w.x << 16), __uint_as_float(w.x & 0xffff0000u), __uint_as_float(w.y << 16), __uint_as_float(w.y & 0xffff0000u)};
;                         x1 = (f32x4){__uint_as_float(w.z << 16), __uint_as_float(w.z & 0xffff0000u), __uint_as_float(w.w << 16), __uint_as_float(w.w & 0xffff0000u)}; }
;                     s += (x0[0] * x0[0] + x0[1] * x0[1]) + (x0[2] * x0[2] + x0[3] * x0[3]) + (x1[0] * x1[0] + x1[1] * x1[1]) + (x1[2] * x1[2] + x1[3] * x1[3]); }
;                 s += __shfl_xor(s, 16); s += __shfl_xor(s, 32);
;                 if (fq == 0) xt[(ai * HALF + wr * 64 + m * 16 + fr) * 4 + wc] = s; }
.LBB0_689:
	s_lshl_b32 s19, s16, 8
	v_add_u32_e32 v142, s19, v147
	v_ashrrev_i32_e32 v143, 31, v142
	v_lshl_add_u32 v140, s18, 8, v146
	v_lshlrev_b64 v[144:145], 12, v[142:143]
	v_ashrrev_i32_e32 v141, 31, v140
	v_cvt_pk_bf16_f32 v154, v0, v1
	v_lshl_add_u64 v[144:145], s[2:3], 0, v[144:145]
	v_cvt_pk_bf16_f32 v155, v2, v3
	v_cvt_pk_bf16_f32 v156, v4, v5
	v_cvt_pk_bf16_f32 v157, v6, v7
	v_lshl_add_u64 v[144:145], v[140:141], 1, v[144:145]
	global_store_dwordx4 v[144:145], v[154:157], off
	s_nop 1
	v_lshlrev_b32_e32 v153, 16, v154
	v_and_b32_e32 v154, 0xffff0000, v154
	v_lshlrev_b32_e32 v158, 16, v155
	v_and_b32_e32 v155, 0xffff0000, v155
	v_mul_f32_e32 v154, v154, v154
	v_fmac_f32_e32 v154, v153, v153
	v_mul_f32_e32 v153, v155, v155
	v_lshlrev_b32_e32 v159, 16, v156
	v_and_b32_e32 v156, 0xffff0000, v156
	v_fmac_f32_e32 v153, v158, v158
	v_add_f32_e32 v153, v154, v153
	v_mul_f32_e32 v154, v156, v156
	v_lshlrev_b32_e32 v160, 16, v157
	v_and_b32_e32 v157, 0xffff0000, v157
	v_fmac_f32_e32 v154, v159, v159
	v_add_f32_e32 v153, v153, v154
	v_mul_f32_e32 v154, v157, v157
	v_fmac_f32_e32 v154, v160, v160
	v_lshl_add_u64 v[144:145], v[144:145], 0, s[24:25]
	v_add_f32_e32 v153, v154, v153
	v_cvt_pk_bf16_f32 v154, v8, v9
	v_cvt_pk_bf16_f32 v155, v10, v11
	v_cvt_pk_bf16_f32 v156, v12, v13
	v_cvt_pk_bf16_f32 v157, v14, v15
	s_nop 0
	global_store_dwordx4 v[144:145], v[154:157], off
	s_nop 1
	v_and_b32_e32 v145, 0xffff0000, v154
	v_lshlrev_b32_e32 v144, 16, v154
	v_lshlrev_b32_e32 v154, 16, v155
	v_and_b32_e32 v155, 0xffff0000, v155
	v_mul_f32_e32 v145, v145, v145
	v_fmac_f32_e32 v145, v144, v144
	v_mul_f32_e32 v144, v155, v155
	v_lshlrev_b32_e32 v158, 16, v156
	v_and_b32_e32 v156, 0xffff0000, v156
	v_fmac_f32_e32 v144, v154, v154
	v_add_f32_e32 v144, v145, v144
	v_mul_f32_e32 v145, v156, v156
	v_lshlrev_b32_e32 v159, 16, v157
	v_and_b32_e32 v157, 0xffff0000, v157
	v_fmac_f32_e32 v145, v158, v158
	v_add_f32_e32 v144, v144, v145
	v_mul_f32_e32 v145, v157, v157
	v_fmac_f32_e32 v145, v159, v159
	v_add_f32_e32 v144, v145, v144
	v_add_f32_e32 v144, v153, v144
	ds_bpermute_b32 v145, v218, v144
	s_waitcnt lgkmcnt(0)
	v_add_f32_e32 v144, v144, v145
	ds_bpermute_b32 v145, v219, v144
	s_and_saveexec_b64 s[40:41], s[0:1]
	s_cbranch_execz .LBB0_691
	s_waitcnt lgkmcnt(0)
	v_add_f32_e32 v144, v144, v145
	ds_write_b32 v152, v144
.LBB0_691:
	s_or_b64 exec, exec, s[40:41]
	v_or_b32_e32 v144, 16, v142
	s_waitcnt lgkmcnt(0)
	v_ashrrev_i32_e32 v145, 31, v144
	v_lshlrev_b64 v[144:145], 12, v[144:145]
	v_cvt_pk_bf16_f32 v154, v16, v17
	v_lshl_add_u64 v[144:145], s[2:3], 0, v[144:145]
	v_cvt_pk_bf16_f32 v155, v18, v19
	v_cvt_pk_bf16_f32 v156, v20, v21
	v_cvt_pk_bf16_f32 v157, v22, v23
	v_lshl_add_u64 v[144:145], v[140:141], 1, v[144:145]
	global_store_dwordx4 v[144:145], v[154:157], off
	s_nop 1
	v_lshlrev_b32_e32 v153, 16, v154
	v_and_b32_e32 v154, 0xffff0000, v154
	v_lshlrev_b32_e32 v158, 16, v155
	v_and_b32_e32 v155, 0xffff0000, v155
	v_mul_f32_e32 v154, v154, v154
	v_fmac_f32_e32 v154, v153, v153
	v_mul_f32_e32 v153, v155, v155
	v_lshlrev_b32_e32 v159, 16, v156
	v_and_b32_e32 v156, 0xffff0000, v156
	v_fmac_f32_e32 v153, v158, v158
	v_add_f32_e32 v153, v154, v153
	v_mul_f32_e32 v154, v156, v156
	v_lshlrev_b32_e32 v160, 16, v157
	v_and_b32_e32 v157, 0xffff0000, v157
	v_fmac_f32_e32 v154, v159, v159
	v_add_f32_e32 v153, v153, v154
	v_mul_f32_e32 v154, v157, v157
	v_fmac_f32_e32 v154, v160, v160
	v_lshl_add_u64 v[144:145], v[144:145], 0, s[24:25]
	v_add_f32_e32 v153, v154, v153
	v_cvt_pk_bf16_f32 v154, v24, v25
	v_cvt_pk_bf16_f32 v155, v26, v27
	v_cvt_pk_bf16_f32 v156, v28, v29
	v_cvt_pk_bf16_f32 v157, v30, v31
	s_nop 0
	global_store_dwordx4 v[144:145], v[154:157], off
	s_nop 1
	v_and_b32_e32 v145, 0xffff0000, v154
	v_lshlrev_b32_e32 v144, 16, v154
	v_lshlrev_b32_e32 v154, 16, v155
	v_and_b32_e32 v155, 0xffff0000, v155
	v_mul_f32_e32 v145, v145, v145
	v_fmac_f32_e32 v145, v144, v144
	v_mul_f32_e32 v144, v155, v155
	v_lshlrev_b32_e32 v158, 16, v156
	v_and_b32_e32 v156, 0xffff0000, v156
	v_fmac_f32_e32 v144, v154, v154
	v_add_f32_e32 v144, v145, v144
	v_mul_f32_e32 v145, v156, v156
	v_lshlrev_b32_e32 v159, 16, v157
	v_and_b32_e32 v157, 0xffff0000, v157
	v_fmac_f32_e32 v145, v158, v158
	v_add_f32_e32 v144, v144, v145
	v_mul_f32_e32 v145, v157, v157
	v_fmac_f32_e32 v145, v159, v159
	v_add_f32_e32 v144, v145, v144
	v_add_f32_e32 v144, v153, v144
	ds_bpermute_b32 v145, v218, v144
	s_waitcnt lgkmcnt(0)
	v_add_f32_e32 v144, v144, v145
	ds_bpermute_b32 v145, v219, v144
	s_and_saveexec_b64 s[40:41], s[0:1]
	s_cbranch_execz .LBB0_693
	s_waitcnt lgkmcnt(0)
	v_add_f32_e32 v144, v144, v145
	ds_write_b32 v152, v144 offset:256
; __device__ __forceinline__ unsigned cvt_pk_bf16(float lo, float hi) { unsigned r; asm volatile("v_cvt_pk_bf16_f32 %0, %1, %2" : "=v"(r) : "v"(lo), "v"(hi)); return r; }
;     __device__ __forceinline__ void operator()(const f32x4 (&acc)[2][2][4][2], const Unit& u, int wr, int wc, int fr, int fq, PG8_LAS float* xt) const {
;     ...
;             for (int m = 0; m < 4; ++m) { const int row = row0 + ai * HALF + m * 16; const size_t off = (size_t)row * 2048 + col0; float s = 0.f;
; #pragma unroll
;                 for (int bj = 0; bj < 2; ++bj) { const size_t o2 = off + bj * HALF;
;                     f32x4 x0 = acc[ai][bj][m][0] * f, x1 = acc[ai][bj][m][1] * f;
;                     if (out_f32) { *(f32x4*)(xout + o2) = x0; *(f32x4*)(xout + o2 + 4) = x1; }
;                     else { u32x4 w; w.x = cvt_pk_bf16(x0[0], x0[1]); w.y = cvt_pk_bf16(x0[2], x0[3]); w.z = cvt_pk_bf16(x1[0], x1[1]); w.w = cvt_pk_bf16(x1[2], x1[3]);
;                         asm volatile("global_store_dwordx4 %0, %1, off sc1\n\ts_nop 1" :: "v"(xb + o2), "v"(w) : "memory");
;                         x0 = (f32x4){__uint_as_float(w.x << 16), __uint_as_float(w.x & 0xffff0000u), __uint_as_float(w.y << 16), __uint_as_float(w.y & 0xffff0000u)};
;                         x1 = (f32x4){__uint_as_float(w.z << 16), __uint_as_float(w.z & 0xffff0000u), __uint_as_float(w.w << 16), __uint_as_float(w.w & 0xffff0000u)}; }
;                     s += (x0[0] * x0[0] + x0[1] * x0[1]) + (x0[2] * x0[2] + x0[3] * x0[3]) + (x1[0] * x1[0] + x1[1] * x1[1]) + (x1[2] * x1[2] + x1[3] * x1[3]); }
;                 s += __shfl_xor(s, 16); s += __shfl_xor(s, 32);
;                 if (fq == 0) xt[(ai * HALF + wr * 64 + m * 16 + fr) * 4 + wc] = s; }
.LBB0_693:
	s_or_b64 exec, exec, s[40:41]
	v_or_b32_e32 v144, 32, v142
	s_waitcnt lgkmcnt(0)
	v_ashrrev_i32_e32 v145, 31, v144
	v_lshlrev_b64 v[144:145], 12, v[144:145]
	v_cvt_pk_bf16_f32 v154, v32, v33
	v_lshl_add_u64 v[144:145], s[2:3], 0, v[144:145]
	v_cvt_pk_bf16_f32 v155, v34, v35
	v_cvt_pk_bf16_f32 v156, v36, v37
	v_cvt_pk_bf16_f32 v157, v38, v39
	v_lshl_add_u64 v[144:145], v[140:141], 1, v[144:145]
	global_store_dwordx4 v[144:145], v[154:157], off
	s_nop 1
	v_lshlrev_b32_e32 v153, 16, v154
	v_and_b32_e32 v154, 0xffff0000, v154
	v_lshlrev_b32_e32 v158, 16, v155
	v_and_b32_e32 v155, 0xffff0000, v155
	v_mul_f32_e32 v154, v154, v154
	v_fmac_f32_e32 v154, v153, v153
	v_mul_f32_e32 v153, v155, v155
	v_lshlrev_b32_e32 v159, 16, v156
	v_and_b32_e32 v156, 0xffff0000, v156
	v_fmac_f32_e32 v153, v158, v158
	v_add_f32_e32 v153, v154, v153
	v_mul_f32_e32 v154, v156, v156
	v_lshlrev_b32_e32 v160, 16, v157
	v_and_b32_e32 v157, 0xffff0000, v157
	v_fmac_f32_e32 v154, v159, v159
	v_add_f32_e32 v153, v153, v154
	v_mul_f32_e32 v154, v157, v157
	v_fmac_f32_e32 v154, v160, v160
	v_lshl_add_u64 v[144:145], v[144:145], 0, s[24:25]
	v_add_f32_e32 v153, v154, v153
	v_cvt_pk_bf16_f32 v154, v40, v41
	v_cvt_pk_bf16_f32 v155, v42, v43
	v_cvt_pk_bf16_f32 v156, v44, v45
	v_cvt_pk_bf16_f32 v157, v46, v47
	s_nop 0
	global_store_dwordx4 v[144:145], v[154:157], off
	s_nop 1
	v_and_b32_e32 v145, 0xffff0000, v154
	v_lshlrev_b32_e32 v144, 16, v154
	v_lshlrev_b32_e32 v154, 16, v155
	v_and_b32_e32 v155, 0xffff0000, v155
	v_mul_f32_e32 v145, v145, v145
	v_fmac_f32_e32 v145, v144, v144
	v_mul_f32_e32 v144, v155, v155
	v_lshlrev_b32_e32 v158, 16, v156
	v_and_b32_e32 v156, 0xffff0000, v156
	v_fmac_f32_e32 v144, v154, v154
	v_add_f32_e32 v144, v145, v144
	v_mul_f32_e32 v145, v156, v156
	v_lshlrev_b32_e32 v159, 16, v157
	v_and_b32_e32 v157, 0xffff0000, v157
	v_fmac_f32_e32 v145, v158, v158
	v_add_f32_e32 v144, v144, v145
	v_mul_f32_e32 v145, v157, v157
	v_fmac_f32_e32 v145, v159, v159
	v_add_f32_e32 v144, v145, v144
	v_add_f32_e32 v144, v153, v144
	ds_bpermute_b32 v145, v218, v144
	s_waitcnt lgkmcnt(0)
	v_add_f32_e32 v144, v144, v145
	ds_bpermute_b32 v145, v219, v144
	s_and_saveexec_b64 s[40:41], s[0:1]
	s_cbranch_execz .LBB0_695
	s_waitcnt lgkmcnt(0)
	v_add_f32_e32 v144, v144, v145
	ds_write_b32 v152, v144 offset:512
.LBB0_695:
	s_or_b64 exec, exec, s[40:41]
	v_or_b32_e32 v144, 48, v142
	s_waitcnt lgkmcnt(0)
	v_ashrrev_i32_e32 v145, 31, v144
	v_lshlrev_b64 v[144:145], 12, v[144:145]
	v_cvt_pk_bf16_f32 v154, v48, v49
	v_lshl_add_u64 v[144:145], s[2:3], 0, v[144:145]
	v_cvt_pk_bf16_f32 v155, v50, v51
	v_cvt_pk_bf16_f32 v156, v52, v53
	v_cvt_pk_bf16_f32 v157, v54, v55
	v_lshl_add_u64 v[144:145], v[140:141], 1, v[144:145]
	global_store_dwordx4 v[144:145], v[154:157], off
	s_nop 1
	v_lshlrev_b32_e32 v153, 16, v154
	v_and_b32_e32 v154, 0xffff0000, v154
	v_lshlrev_b32_e32 v158, 16, v155
	v_and_b32_e32 v155, 0xffff0000, v155
	v_mul_f32_e32 v154, v154, v154
	v_fmac_f32_e32 v154, v153, v153
	v_mul_f32_e32 v153, v155, v155
	v_lshlrev_b32_e32 v159, 16, v156
	v_and_b32_e32 v156, 0xffff0000, v156
	v_fmac_f32_e32 v153, v158, v158
	v_add_f32_e32 v153, v154, v153
	v_mul_f32_e32 v154, v156, v156
	v_lshlrev_b32_e32 v160, 16, v157
	v_and_b32_e32 v157, 0xffff0000, v157
	v_fmac_f32_e32 v154, v159, v159
	v_add_f32_e32 v153, v153, v154
	v_mul_f32_e32 v154, v157, v157
	v_fmac_f32_e32 v154, v160, v160
	v_lshl_add_u64 v[144:145], v[144:145], 0, s[24:25]
	v_add_f32_e32 v153, v154, v153
	v_cvt_pk_bf16_f32 v154, v56, v57
	v_cvt_pk_bf16_f32 v155, v58, v59
	v_cvt_pk_bf16_f32 v156, v60, v61
	v_cvt_pk_bf16_f32 v157, v62, v63
	s_nop 0
	global_store_dwordx4 v[144:145], v[154:157], off
	s_nop 1
	v_and_b32_e32 v145, 0xffff0000, v154
	v_lshlrev_b32_e32 v144, 16, v154
	v_lshlrev_b32_e32 v154, 16, v155
	v_and_b32_e32 v155, 0xffff0000, v155
	v_mul_f32_e32 v145, v145, v145
	v_fmac_f32_e32 v145, v144, v144
	v_mul_f32_e32 v144, v155, v155
	v_lshlrev_b32_e32 v158, 16, v156
	v_and_b32_e32 v156, 0xffff0000, v156
	v_fmac_f32_e32 v144, v154, v154
	v_add_f32_e32 v144, v145, v144
	v_mul_f32_e32 v145, v156, v156
	v_lshlrev_b32_e32 v159, 16, v157
	v_and_b32_e32 v157, 0xffff0000, v157
	v_fmac_f32_e32 v145, v158, v158
	v_add_f32_e32 v144, v144, v145
	v_mul_f32_e32 v145, v157, v157
	v_fmac_f32_e32 v145, v159, v159
	v_add_f32_e32 v144, v145, v144
	v_add_f32_e32 v144, v153, v144
	ds_bpermute_b32 v145, v218, v144
	s_waitcnt lgkmcnt(0)
	v_add_f32_e32 v144, v144, v145
	ds_bpermute_b32 v145, v219, v144
	s_and_saveexec_b64 s[40:41], s[0:1]
	s_cbranch_execz .LBB0_697
	s_waitcnt lgkmcnt(0)
	v_add_f32_e32 v144, v144, v145
	ds_write_b32 v152, v144 offset:768
; __device__ __forceinline__ unsigned cvt_pk_bf16(float lo, float hi) { unsigned r; asm volatile("v_cvt_pk_bf16_f32 %0, %1, %2" : "=v"(r) : "v"(lo), "v"(hi)); return r; }
;     __device__ __forceinline__ void operator()(const f32x4 (&acc)[2][2][4][2], const Unit& u, int wr, int wc, int fr, int fq, PG8_LAS float* xt) const {
;     ...
;             for (int m = 0; m < 4; ++m) { const int row = row0 + ai * HALF + m * 16; const size_t off = (size_t)row * 2048 + col0; float s = 0.f;
; #pragma unroll
;                 for (int bj = 0; bj < 2; ++bj) { const size_t o2 = off + bj * HALF;
;                     f32x4 x0 = acc[ai][bj][m][0] * f, x1 = acc[ai][bj][m][1] * f;
;                     if (out_f32) { *(f32x4*)(xout + o2) = x0; *(f32x4*)(xout + o2 + 4) = x1; }
;                     else { u32x4 w; w.x = cvt_pk_bf16(x0[0], x0[1]); w.y = cvt_pk_bf16(x0[2], x0[3]); w.z = cvt_pk_bf16(x1[0], x1[1]); w.w = cvt_pk_bf16(x1[2], x1[3]);
;                         asm volatile("global_store_dwordx4 %0, %1, off sc1\n\ts_nop 1" :: "v"(xb + o2), "v"(w) : "memory");
;                         x0 = (f32x4){__uint_as_float(w.x << 16), __uint_as_float(w.x & 0xffff0000u), __uint_as_float(w.y << 16), __uint_as_float(w.y & 0xffff0000u)};
;                         x1 = (f32x4){__uint_as_float(w.z << 16), __uint_as_float(w.z & 0xffff0000u), __uint_as_float(w.w << 16), __uint_as_float(w.w & 0xffff0000u)}; }
;                     s += (x0[0] * x0[0] + x0[1] * x0[1]) + (x0[2] * x0[2] + x0[3] * x0[3]) + (x1[0] * x1[0] + x1[1] * x1[1]) + (x1[2] * x1[2] + x1[3] * x1[3]); }
;                 s += __shfl_xor(s, 16); s += __shfl_xor(s, 32);
;                 if (fq == 0) xt[(ai * HALF + wr * 64 + m * 16 + fr) * 4 + wc] = s; }
.LBB0_697:
	s_or_b64 exec, exec, s[40:41]
	s_waitcnt lgkmcnt(0)
	v_lshlrev_b64 v[144:145], 12, v[142:143]
	v_lshl_add_u64 v[144:145], s[2:3], 0, v[144:145]
	v_cvt_pk_bf16_f32 v154, v64, v65
	v_lshl_add_u64 v[144:145], v[140:141], 1, v[144:145]
	v_cvt_pk_bf16_f32 v155, v66, v67
	v_cvt_pk_bf16_f32 v156, v68, v69
	v_cvt_pk_bf16_f32 v157, v70, v71
	v_lshl_add_u64 v[158:159], v[144:145], 0, s[74:75]
	global_store_dwordx4 v[158:159], v[154:157], off
	s_nop 1
	v_lshlrev_b32_e32 v153, 16, v154
	v_and_b32_e32 v154, 0xffff0000, v154
	v_lshlrev_b32_e32 v158, 16, v155
	v_and_b32_e32 v155, 0xffff0000, v155
	v_mul_f32_e32 v154, v154, v154
	v_fmac_f32_e32 v154, v153, v153
	v_mul_f32_e32 v153, v155, v155
	v_lshlrev_b32_e32 v159, 16, v156
	v_and_b32_e32 v156, 0xffff0000, v156
	v_fmac_f32_e32 v153, v158, v158
	v_add_f32_e32 v153, v154, v153
	v_mul_f32_e32 v154, v156, v156
	v_lshlrev_b32_e32 v160, 16, v157
	v_and_b32_e32 v157, 0xffff0000, v157
	v_fmac_f32_e32 v154, v159, v159
	v_add_f32_e32 v153, v153, v154
	v_mul_f32_e32 v154, v157, v157
	v_fmac_f32_e32 v154, v160, v160
	s_mov_b64 s[40:41], 0x80100
	v_add_f32_e32 v153, v154, v153
	v_cvt_pk_bf16_f32 v154, v72, v73
	v_cvt_pk_bf16_f32 v155, v74, v75
	v_lshl_add_u64 v[158:159], v[144:145], 0, s[40:41]
	v_cvt_pk_bf16_f32 v156, v76, v77
	v_cvt_pk_bf16_f32 v157, v78, v79
	s_nop 0
	global_store_dwordx4 v[158:159], v[154:157], off
	s_nop 1
	v_lshlrev_b32_e32 v158, 16, v154
	v_and_b32_e32 v154, 0xffff0000, v154
	v_lshlrev_b32_e32 v159, 16, v155
	v_and_b32_e32 v155, 0xffff0000, v155
	v_mul_f32_e32 v154, v154, v154
	v_mul_f32_e32 v155, v155, v155
	v_lshlrev_b32_e32 v160, 16, v156
	v_and_b32_e32 v156, 0xffff0000, v156
	v_fmac_f32_e32 v154, v158, v158
	v_fmac_f32_e32 v155, v159, v159
	v_add_f32_e32 v154, v154, v155
	v_mul_f32_e32 v155, v156, v156
	v_lshlrev_b32_e32 v161, 16, v157
	v_and_b32_e32 v157, 0xffff0000, v157
	v_fmac_f32_e32 v155, v160, v160
	v_add_f32_e32 v154, v154, v155
	v_mul_f32_e32 v155, v157, v157
	v_fmac_f32_e32 v155, v161, v161
	v_add_f32_e32 v154, v155, v154
	v_add_f32_e32 v153, v153, v154
	ds_bpermute_b32 v154, v218, v153
	s_waitcnt lgkmcnt(0)
	v_add_f32_e32 v153, v153, v154
	ds_bpermute_b32 v154, v219, v153
	s_and_saveexec_b64 s[40:41], s[0:1]
	s_cbranch_execz .LBB0_699
	s_waitcnt lgkmcnt(0)
	v_add_f32_e32 v153, v153, v154
	ds_write_b32 v152, v153 offset:2048
.LBB0_699:
	s_or_b64 exec, exec, s[40:41]
	s_waitcnt lgkmcnt(0)
	v_cvt_pk_bf16_f32 v154, v80, v81
	s_mov_b64 s[40:41], 0x90000
	v_cvt_pk_bf16_f32 v155, v82, v83
	v_cvt_pk_bf16_f32 v156, v84, v85
	v_cvt_pk_bf16_f32 v157, v86, v87
	v_lshl_add_u64 v[158:159], v[144:145], 0, s[40:41]
	global_store_dwordx4 v[158:159], v[154:157], off
	s_nop 1
	v_lshlrev_b32_e32 v153, 16, v154
	v_and_b32_e32 v154, 0xffff0000, v154
	v_lshlrev_b32_e32 v158, 16, v155
	v_and_b32_e32 v155, 0xffff0000, v155
	v_mul_f32_e32 v154, v154, v154
	v_fmac_f32_e32 v154, v153, v153
	v_mul_f32_e32 v153, v155, v155
	v_lshlrev_b32_e32 v159, 16, v156
	v_and_b32_e32 v156, 0xffff0000, v156
	v_fmac_f32_e32 v153, v158, v158
	v_add_f32_e32 v153, v154, v153
	v_mul_f32_e32 v154, v156, v156
	v_lshlrev_b32_e32 v160, 16, v157
	v_and_b32_e32 v157, 0xffff0000, v157
	v_fmac_f32_e32 v154, v159, v159
	v_add_f32_e32 v153, v153, v154
	v_mul_f32_e32 v154, v157, v157
	s_mov_b64 s[40:41], 0x90100
	v_fmac_f32_e32 v154, v160, v160
	v_lshl_add_u64 v[144:145], v[144:145], 0, s[40:41]
	v_add_f32_e32 v153, v154, v153
	v_cvt_pk_bf16_f32 v154, v88, v89
	v_cvt_pk_bf16_f32 v155, v90, v91
	v_cvt_pk_bf16_f32 v156, v92, v93
	v_cvt_pk_bf16_f32 v157, v94, v95
	s_nop 0
	global_store_dwordx4 v[144:145], v[154:157], off
	s_nop 1
	v_and_b32_e32 v145, 0xffff0000, v154
	v_lshlrev_b32_e32 v144, 16, v154
	v_lshlrev_b32_e32 v154, 16, v155
	v_and_b32_e32 v155, 0xffff0000, v155
	v_mul_f32_e32 v145, v145, v145
	v_fmac_f32_e32 v145, v144, v144
	v_mul_f32_e32 v144, v155, v155
	v_lshlrev_b32_e32 v158, 16, v156
	v_and_b32_e32 v156, 0xffff0000, v156
	v_fmac_f32_e32 v144, v154, v154
	v_add_f32_e32 v144, v145, v144
	v_mul_f32_e32 v145, v156, v156
	v_lshlrev_b32_e32 v159, 16, v157
	v_and_b32_e32 v157, 0xffff0000, v157
	v_fmac_f32_e32 v145, v158, v158
	v_add_f32_e32 v144, v144, v145
	v_mul_f32_e32 v145, v157, v157
	v_fmac_f32_e32 v145, v159, v159
	v_add_f32_e32 v144, v145, v144
	v_add_f32_e32 v144, v153, v144
	ds_bpermute_b32 v145, v218, v144
	s_waitcnt lgkmcnt(0)
	v_add_f32_e32 v144, v144, v145
	ds_bpermute_b32 v145, v219, v144
	s_and_saveexec_b64 s[40:41], s[0:1]
	s_cbranch_execz .LBB0_701
	s_waitcnt lgkmcnt(0)
	v_add_f32_e32 v144, v144, v145
	ds_write_b32 v152, v144 offset:2304
; __device__ __forceinline__ unsigned cvt_pk_bf16(float lo, float hi) { unsigned r; asm volatile("v_cvt_pk_bf16_f32 %0, %1, %2" : "=v"(r) : "v"(lo), "v"(hi)); return r; }
;     __device__ __forceinline__ void operator()(const f32x4 (&acc)[2][2][4][2], const Unit& u, int wr, int wc, int fr, int fq, PG8_LAS float* xt) const {
;     ...
;             for (int m = 0; m < 4; ++m) { const int row = row0 + ai * HALF + m * 16; const size_t off = (size_t)row * 2048 + col0; float s = 0.f;
; #pragma unroll
;                 for (int bj = 0; bj < 2; ++bj) { const size_t o2 = off + bj * HALF;
;                     f32x4 x0 = acc[ai][bj][m][0] * f, x1 = acc[ai][bj][m][1] * f;
;                     if (out_f32) { *(f32x4*)(xout + o2) = x0; *(f32x4*)(xout + o2 + 4) = x1; }
;                     else { u32x4 w; w.x = cvt_pk_bf16(x0[0], x0[1]); w.y = cvt_pk_bf16(x0[2], x0[3]); w.z = cvt_pk_bf16(x1[0], x1[1]); w.w = cvt_pk_bf16(x1[2], x1[3]);
;                         asm volatile("global_store_dwordx4 %0, %1, off sc1\n\ts_nop 1" :: "v"(xb + o2), "v"(w) : "memory");
;                         x0 = (f32x4){__uint_as_float(w.x << 16), __uint_as_float(w.x & 0xffff0000u), __uint_as_float(w.y << 16), __uint_as_float(w.y & 0xffff0000u)};
;                         x1 = (f32x4){__uint_as_float(w.z << 16), __uint_as_float(w.z & 0xffff0000u), __uint_as_float(w.w << 16), __uint_as_float(w.w & 0xffff0000u)}; }
;                     s += (x0[0] * x0[0] + x0[1] * x0[1]) + (x0[2] * x0[2] + x0[3] * x0[3]) + (x1[0] * x1[0] + x1[1] * x1[1]) + (x1[2] * x1[2] + x1[3] * x1[3]); }
;                 s += __shfl_xor(s, 16); s += __shfl_xor(s, 32);
;                 if (fq == 0) xt[(ai * HALF + wr * 64 + m * 16 + fr) * 4 + wc] = s; }
.LBB0_701:
	s_or_b64 exec, exec, s[40:41]
	v_lshlrev_b64 v[154:155], 12, v[142:143]
	v_lshl_add_u64 v[154:155], s[2:3], 0, v[154:155]
	v_lshl_add_u64 v[140:141], v[140:141], 1, v[154:155]
	s_mov_b64 s[40:41], 0xa0000
	v_cvt_pk_bf16_f32 v142, v98, v99
	v_cvt_pk_bf16_f32 v143, v100, v101
	v_lshl_add_u64 v[154:155], v[140:141], 0, s[40:41]
	v_cvt_pk_bf16_f32 v144, v102, v103
	s_waitcnt lgkmcnt(0)
	v_cvt_pk_bf16_f32 v145, v104, v105
	v_lshlrev_b32_e32 v153, 16, v142
	global_store_dwordx4 v[154:155], v[142:145], off
	s_nop 1
	v_and_b32_e32 v142, 0xffff0000, v142
	v_lshlrev_b32_e32 v154, 16, v143
	v_and_b32_e32 v143, 0xffff0000, v143
	v_mul_f32_e32 v142, v142, v142
	v_mul_f32_e32 v143, v143, v143
	v_lshlrev_b32_e32 v155, 16, v144
	v_and_b32_e32 v144, 0xffff0000, v144
	v_fmac_f32_e32 v142, v153, v153
	v_fmac_f32_e32 v143, v154, v154
	v_add_f32_e32 v142, v142, v143
	v_mul_f32_e32 v143, v144, v144
	v_lshlrev_b32_e32 v156, 16, v145
	v_and_b32_e32 v145, 0xffff0000, v145
	v_fmac_f32_e32 v143, v155, v155
	v_add_f32_e32 v142, v142, v143
	v_mul_f32_e32 v143, v145, v145
	v_fmac_f32_e32 v143, v156, v156
	s_mov_b64 s[40:41], 0xa0100
	v_add_f32_e32 v153, v143, v142
	v_cvt_pk_bf16_f32 v142, v106, v107
	v_cvt_pk_bf16_f32 v143, v108, v109
	v_lshl_add_u64 v[154:155], v[140:141], 0, s[40:41]
	v_cvt_pk_bf16_f32 v144, v110, v111
	v_cvt_pk_bf16_f32 v145, v112, v113
	s_nop 0
	global_store_dwordx4 v[154:155], v[142:145], off
	s_nop 1
	v_lshlrev_b32_e32 v154, 16, v142
	v_and_b32_e32 v142, 0xffff0000, v142
	v_lshlrev_b32_e32 v155, 16, v143
	v_and_b32_e32 v143, 0xffff0000, v143
	v_mul_f32_e32 v142, v142, v142
	v_mul_f32_e32 v143, v143, v143
	v_lshlrev_b32_e32 v156, 16, v144
	v_and_b32_e32 v144, 0xffff0000, v144
	v_fmac_f32_e32 v142, v154, v154
	v_fmac_f32_e32 v143, v155, v155
	v_add_f32_e32 v142, v142, v143
	v_mul_f32_e32 v143, v144, v144
	v_lshlrev_b32_e32 v157, 16, v145
	v_and_b32_e32 v145, 0xffff0000, v145
	v_fmac_f32_e32 v143, v156, v156
	v_add_f32_e32 v142, v142, v143
	v_mul_f32_e32 v143, v145, v145
	v_fmac_f32_e32 v143, v157, v157
	v_add_f32_e32 v142, v143, v142
	v_add_f32_e32 v142, v153, v142
	ds_bpermute_b32 v143, v218, v142
	s_waitcnt lgkmcnt(0)
	v_add_f32_e32 v142, v142, v143
	ds_bpermute_b32 v143, v219, v142
	s_and_saveexec_b64 s[40:41], s[0:1]
	s_cbranch_execz .LBB0_703
	s_waitcnt lgkmcnt(0)
	v_add_f32_e32 v142, v142, v143
	ds_write_b32 v152, v142 offset:2560
.LBB0_703:
	s_or_b64 exec, exec, s[40:41]
	s_mov_b64 s[40:41], 0xb0000
	v_cvt_pk_bf16_f32 v142, v114, v115
	s_waitcnt lgkmcnt(0)
	v_cvt_pk_bf16_f32 v143, v116, v117
	v_lshl_add_u64 v[154:155], v[140:141], 0, s[40:41]
	v_cvt_pk_bf16_f32 v144, v118, v119
	v_cvt_pk_bf16_f32 v145, v120, v121
	v_lshlrev_b32_e32 v153, 16, v142
	global_store_dwordx4 v[154:155], v[142:145], off
	s_nop 1
	v_and_b32_e32 v142, 0xffff0000, v142
	v_lshlrev_b32_e32 v154, 16, v143
	v_and_b32_e32 v143, 0xffff0000, v143
	v_mul_f32_e32 v142, v142, v142
	v_mul_f32_e32 v143, v143, v143
	v_lshlrev_b32_e32 v155, 16, v144
	v_and_b32_e32 v144, 0xffff0000, v144
	v_fmac_f32_e32 v142, v153, v153
	v_fmac_f32_e32 v143, v154, v154
	v_add_f32_e32 v142, v142, v143
	v_mul_f32_e32 v143, v144, v144
	v_lshlrev_b32_e32 v156, 16, v145
	v_and_b32_e32 v145, 0xffff0000, v145
	v_fmac_f32_e32 v143, v155, v155
	v_add_f32_e32 v142, v142, v143
	v_mul_f32_e32 v143, v145, v145
	s_mov_b64 s[40:41], 0xb0100
	v_fmac_f32_e32 v143, v156, v156
	v_lshl_add_u64 v[140:141], v[140:141], 0, s[40:41]
	v_add_f32_e32 v153, v143, v142
	v_cvt_pk_bf16_f32 v142, v122, v123
	v_cvt_pk_bf16_f32 v143, v124, v125
	v_cvt_pk_bf16_f32 v144, v126, v127
	v_cvt_pk_bf16_f32 v145, v128, v129
	s_nop 0
	global_store_dwordx4 v[140:141], v[142:145], off
	s_nop 1
	v_and_b32_e32 v141, 0xffff0000, v142
	v_lshlrev_b32_e32 v140, 16, v142
	v_lshlrev_b32_e32 v142, 16, v143
	v_and_b32_e32 v143, 0xffff0000, v143
	v_mul_f32_e32 v141, v141, v141
	v_fmac_f32_e32 v141, v140, v140
	v_mul_f32_e32 v140, v143, v143
	v_lshlrev_b32_e32 v154, 16, v144
	v_and_b32_e32 v144, 0xffff0000, v144
	v_fmac_f32_e32 v140, v142, v142
	v_add_f32_e32 v140, v141, v140
	v_mul_f32_e32 v141, v144, v144
	v_lshlrev_b32_e32 v155, 16, v145
	v_and_b32_e32 v145, 0xffff0000, v145
	v_fmac_f32_e32 v141, v154, v154
	v_add_f32_e32 v140, v140, v141
	v_mul_f32_e32 v141, v145, v145
	v_fmac_f32_e32 v141, v155, v155
	v_add_f32_e32 v140, v141, v140
	v_add_f32_e32 v140, v153, v140
	ds_bpermute_b32 v141, v218, v140
	s_waitcnt lgkmcnt(0)
	v_add_f32_e32 v140, v140, v141
	ds_bpermute_b32 v141, v219, v140
	s_and_saveexec_b64 s[40:41], s[0:1]
	s_cbranch_execz .LBB0_705
	s_waitcnt lgkmcnt(0)
	v_add_f32_e32 v140, v140, v141
	ds_write_b32 v152, v140 offset:2816

; __device__ __forceinline__ unsigned cvt_pk_bf16(float lo, float hi) { unsigned r; asm volatile("v_cvt_pk_bf16_f32 %0, %1, %2" : "=v"(r) : "v"(lo), "v"(hi)); return r; }
;     __device__ __forceinline__ void operator()(const f32x4 (&acc)[2][2][4][2], const Unit& u, int wr, int wc, int fr, int fq, PG8_LAS float* xt) const {
;     ...
;             for (int m = 0; m < 4; ++m) { const int row = row0 + ai * HALF + m * 16; const size_t off = (size_t)row * 2048 + col0; float s = 0.f;
; #pragma unroll
;                 for (int bj = 0; bj < 2; ++bj) { const size_t o2 = off + bj * HALF;
;                     f32x4 x0 = acc[ai][bj][m][0] * f, x1 = acc[ai][bj][m][1] * f;
;                     if (out_f32) { *(f32x4*)(xout + o2) = x0; *(f32x4*)(xout + o2 + 4) = x1; }
;                     else { u32x4 w; w.x = cvt_pk_bf16(x0[0], x0[1]); w.y = cvt_pk_bf16(x0[2], x0[3]); w.z = cvt_pk_bf16(x1[0], x1[1]); w.w = cvt_pk_bf16(x1[2], x1[3]);
;                         asm volatile("global_store_dwordx4 %0, %1, off sc1\n\ts_nop 1" :: "v"(xb + o2), "v"(w) : "memory");
;                         x0 = (f32x4){__uint_as_float(w.x << 16), __uint_as_float(w.x & 0xffff0000u), __uint_as_float(w.y << 16), __uint_as_float(w.y & 0xffff0000u)};
;                         x1 = (f32x4){__uint_as_float(w.z << 16), __uint_as_float(w.z & 0xffff0000u), __uint_as_float(w.w << 16), __uint_as_float(w.w & 0xffff0000u)}; }
;                     s += (x0[0] * x0[0] + x0[1] * x0[1]) + (x0[2] * x0[2] + x0[3] * x0[3]) + (x1[0] * x1[0] + x1[1] * x1[1]) + (x1[2] * x1[2] + x1[3] * x1[3]); }
.LBB0_863:
	s_lshl_b32 s3, s6, 8
	v_add_u32_e32 v166, s3, v173
	v_lshl_add_u32 v164, s2, 8, v172
	v_ashrrev_i32_e32 v167, 31, v166
	v_ashrrev_i32_e32 v165, 31, v164
	v_lshlrev_b64 v[130:131], 11, v[166:167]
	v_lshl_add_u64 v[146:147], v[130:131], 0, v[164:165]
	v_pk_mul_f32 v[140:141], v[2:3], 0.5 op_sel_hi:[1,0]
	v_pk_mul_f32 v[138:139], v[0:1], 0.5 op_sel_hi:[1,0]
	v_pk_mul_f32 v[144:145], v[6:7], 0.5 op_sel_hi:[1,0]
	v_pk_mul_f32 v[142:143], v[4:5], 0.5 op_sel_hi:[1,0]
	s_mov_b64 s[28:29], -1
	s_and_b64 vcc, exec, s[64:65]
	v_lshl_add_u64 v[168:169], v[146:147], 1, s[44:45]
	s_cbranch_vccz .LBB0_865
	v_cvt_pk_bf16_f32 v134, v138, v139
	v_cvt_pk_bf16_f32 v135, v140, v141
	v_cvt_pk_bf16_f32 v136, v142, v143
	v_cvt_pk_bf16_f32 v137, v144, v145
	s_mov_b64 s[28:29], 0
	global_store_dwordx4 v[168:169], v[134:137], off
	s_nop 1
	v_lshlrev_b32_e32 v130, 16, v134
	v_and_b32_e32 v131, 0xffff0000, v134
	v_lshlrev_b32_e32 v132, 16, v135
	v_and_b32_e32 v133, 0xffff0000, v135
	v_lshlrev_b32_e32 v134, 16, v136
	v_and_b32_e32 v135, 0xffff0000, v136
	v_lshlrev_b32_e32 v136, 16, v137
	v_and_b32_e32 v137, 0xffff0000, v137

; __device__ __forceinline__ unsigned cvt_pk_bf16(float lo, float hi) { unsigned r; asm volatile("v_cvt_pk_bf16_f32 %0, %1, %2" : "=v"(r) : "v"(lo), "v"(hi)); return r; }
;     __device__ __forceinline__ void operator()(const f32x4 (&acc)[2][2][4][2], const Unit& u, int wr, int wc, int fr, int fq, PG8_LAS float* xt) const {
;     ...
;             for (int m = 0; m < 4; ++m) { const int row = row0 + ai * HALF + m * 16; const size_t off = (size_t)row * 2048 + col0; float s = 0.f;
; #pragma unroll
;                 for (int bj = 0; bj < 2; ++bj) { const size_t o2 = off + bj * HALF;
;                     f32x4 x0 = acc[ai][bj][m][0] * f, x1 = acc[ai][bj][m][1] * f;
;                     if (out_f32) { *(f32x4*)(xout + o2) = x0; *(f32x4*)(xout + o2 + 4) = x1; }
;                     else { u32x4 w; w.x = cvt_pk_bf16(x0[0], x0[1]); w.y = cvt_pk_bf16(x0[2], x0[3]); w.z = cvt_pk_bf16(x1[0], x1[1]); w.w = cvt_pk_bf16(x1[2], x1[3]);
;                         asm volatile("global_store_dwordx4 %0, %1, off sc1\n\ts_nop 1" :: "v"(xb + o2), "v"(w) : "memory");
;                         x0 = (f32x4){__uint_as_float(w.x << 16), __uint_as_float(w.x & 0xffff0000u), __uint_as_float(w.y << 16), __uint_as_float(w.y & 0xffff0000u)};
;                         x1 = (f32x4){__uint_as_float(w.z << 16), __uint_as_float(w.z & 0xffff0000u), __uint_as_float(w.w << 16), __uint_as_float(w.w & 0xffff0000u)}; }
;                     s += (x0[0] * x0[0] + x0[1] * x0[1]) + (x0[2] * x0[2] + x0[3] * x0[3]) + (x1[0] * x1[0] + x1[1] * x1[1]) + (x1[2] * x1[2] + x1[3] * x1[3]); }
.LBB0_867:
	s_nop 0
	v_pk_mul_f32 v[140:141], v[10:11], 0.5 op_sel_hi:[1,0]
	v_pk_mul_f32 v[138:139], v[8:9], 0.5 op_sel_hi:[1,0]
	v_pk_mul_f32 v[144:145], v[14:15], 0.5 op_sel_hi:[1,0]
	v_pk_mul_f32 v[142:143], v[12:13], 0.5 op_sel_hi:[1,0]
	s_mov_b64 s[28:29], -1
	s_and_b64 vcc, exec, s[64:65]
	s_cbranch_vccz .LBB0_869
	v_cvt_pk_bf16_f32 v150, v138, v139
	v_cvt_pk_bf16_f32 v151, v140, v141
	v_cvt_pk_bf16_f32 v152, v142, v143
	v_cvt_pk_bf16_f32 v153, v144, v145
	v_lshl_add_u64 v[146:147], v[168:169], 0, s[24:25]
	global_store_dwordx4 v[146:147], v[150:153], off
	s_nop 1
	v_lshlrev_b32_e32 v146, 16, v150
	v_and_b32_e32 v147, 0xffff0000, v150
	v_lshlrev_b32_e32 v148, 16, v151
	v_and_b32_e32 v149, 0xffff0000, v151
	v_lshlrev_b32_e32 v150, 16, v152
	v_and_b32_e32 v151, 0xffff0000, v152
	v_lshlrev_b32_e32 v152, 16, v153
	v_and_b32_e32 v153, 0xffff0000, v153
	s_mov_b64 s[28:29], 0

; __device__ __forceinline__ unsigned cvt_pk_bf16(float lo, float hi) { unsigned r; asm volatile("v_cvt_pk_bf16_f32 %0, %1, %2" : "=v"(r) : "v"(lo), "v"(hi)); return r; }
;     __device__ __forceinline__ void operator()(const f32x4 (&acc)[2][2][4][2], const Unit& u, int wr, int wc, int fr, int fq, PG8_LAS float* xt) const {
;     ...
;             for (int m = 0; m < 4; ++m) { const int row = row0 + ai * HALF + m * 16; const size_t off = (size_t)row * 2048 + col0; float s = 0.f;
; #pragma unroll
;                 for (int bj = 0; bj < 2; ++bj) { const size_t o2 = off + bj * HALF;
;                     f32x4 x0 = acc[ai][bj][m][0] * f, x1 = acc[ai][bj][m][1] * f;
;                     if (out_f32) { *(f32x4*)(xout + o2) = x0; *(f32x4*)(xout + o2 + 4) = x1; }
;                     else { u32x4 w; w.x = cvt_pk_bf16(x0[0], x0[1]); w.y = cvt_pk_bf16(x0[2], x0[3]); w.z = cvt_pk_bf16(x1[0], x1[1]); w.w = cvt_pk_bf16(x1[2], x1[3]);
;                         asm volatile("global_store_dwordx4 %0, %1, off sc1\n\ts_nop 1" :: "v"(xb + o2), "v"(w) : "memory");
;                         x0 = (f32x4){__uint_as_float(w.x << 16), __uint_as_float(w.x & 0xffff0000u), __uint_as_float(w.y << 16), __uint_as_float(w.y & 0xffff0000u)};
;                         x1 = (f32x4){__uint_as_float(w.z << 16), __uint_as_float(w.z & 0xffff0000u), __uint_as_float(w.w << 16), __uint_as_float(w.w & 0xffff0000u)}; }
;                     s += (x0[0] * x0[0] + x0[1] * x0[1]) + (x0[2] * x0[2] + x0[3] * x0[3]) + (x1[0] * x1[0] + x1[1] * x1[1]) + (x1[2] * x1[2] + x1[3] * x1[3]); }
.LBB0_873:
	s_or_b64 exec, exec, s[28:29]
	v_or_b32_e32 v130, 16, v166
	s_waitcnt lgkmcnt(0)
	v_ashrrev_i32_e32 v131, 31, v130
	v_lshlrev_b64 v[130:131], 11, v[130:131]
	v_lshl_add_u64 v[146:147], v[130:131], 0, v[164:165]
	v_pk_mul_f32 v[140:141], v[18:19], 0.5 op_sel_hi:[1,0]
	v_pk_mul_f32 v[138:139], v[16:17], 0.5 op_sel_hi:[1,0]
	v_pk_mul_f32 v[144:145], v[22:23], 0.5 op_sel_hi:[1,0]
	v_pk_mul_f32 v[142:143], v[20:21], 0.5 op_sel_hi:[1,0]
	s_mov_b64 s[28:29], -1
	s_and_b64 vcc, exec, s[64:65]
	v_lshl_add_u64 v[168:169], v[146:147], 1, s[44:45]
	s_cbranch_vccz .LBB0_875
	v_cvt_pk_bf16_f32 v134, v138, v139
	v_cvt_pk_bf16_f32 v135, v140, v141
	v_cvt_pk_bf16_f32 v136, v142, v143
	v_cvt_pk_bf16_f32 v137, v144, v145
	s_mov_b64 s[28:29], 0
	global_store_dwordx4 v[168:169], v[134:137], off
	s_nop 1
	v_lshlrev_b32_e32 v130, 16, v134
	v_and_b32_e32 v131, 0xffff0000, v134
	v_lshlrev_b32_e32 v132, 16, v135
	v_and_b32_e32 v133, 0xffff0000, v135
	v_lshlrev_b32_e32 v134, 16, v136
	v_and_b32_e32 v135, 0xffff0000, v136
	v_lshlrev_b32_e32 v136, 16, v137
	v_and_b32_e32 v137, 0xffff0000, v137

; __device__ __forceinline__ unsigned cvt_pk_bf16(float lo, float hi) { unsigned r; asm volatile("v_cvt_pk_bf16_f32 %0, %1, %2" : "=v"(r) : "v"(lo), "v"(hi)); return r; }
;     __device__ __forceinline__ void operator()(const f32x4 (&acc)[2][2][4][2], const Unit& u, int wr, int wc, int fr, int fq, PG8_LAS float* xt) const {
;     ...
;             for (int m = 0; m < 4; ++m) { const int row = row0 + ai * HALF + m * 16; const size_t off = (size_t)row * 2048 + col0; float s = 0.f;
; #pragma unroll
;                 for (int bj = 0; bj < 2; ++bj) { const size_t o2 = off + bj * HALF;
;                     f32x4 x0 = acc[ai][bj][m][0] * f, x1 = acc[ai][bj][m][1] * f;
;                     if (out_f32) { *(f32x4*)(xout + o2) = x0; *(f32x4*)(xout + o2 + 4) = x1; }
;                     else { u32x4 w; w.x = cvt_pk_bf16(x0[0], x0[1]); w.y = cvt_pk_bf16(x0[2], x0[3]); w.z = cvt_pk_bf16(x1[0], x1[1]); w.w = cvt_pk_bf16(x1[2], x1[3]);
;                         asm volatile("global_store_dwordx4 %0, %1, off sc1\n\ts_nop 1" :: "v"(xb + o2), "v"(w) : "memory");
;                         x0 = (f32x4){__uint_as_float(w.x << 16), __uint_as_float(w.x & 0xffff0000u), __uint_as_float(w.y << 16), __uint_as_float(w.y & 0xffff0000u)};
;                         x1 = (f32x4){__uint_as_float(w.z << 16), __uint_as_float(w.z & 0xffff0000u), __uint_as_float(w.w << 16), __uint_as_float(w.w & 0xffff0000u)}; }
;                     s += (x0[0] * x0[0] + x0[1] * x0[1]) + (x0[2] * x0[2] + x0[3] * x0[3]) + (x1[0] * x1[0] + x1[1] * x1[1]) + (x1[2] * x1[2] + x1[3] * x1[3]); }
.LBB0_877:
	s_nop 0
	v_pk_mul_f32 v[140:141], v[26:27], 0.5 op_sel_hi:[1,0]
	v_pk_mul_f32 v[138:139], v[24:25], 0.5 op_sel_hi:[1,0]
	v_pk_mul_f32 v[144:145], v[30:31], 0.5 op_sel_hi:[1,0]
	v_pk_mul_f32 v[142:143], v[28:29], 0.5 op_sel_hi:[1,0]
	s_mov_b64 s[28:29], -1
	s_and_b64 vcc, exec, s[64:65]
	s_cbranch_vccz .LBB0_879
	v_cvt_pk_bf16_f32 v150, v138, v139
	v_cvt_pk_bf16_f32 v151, v140, v141
	v_cvt_pk_bf16_f32 v152, v142, v143
	v_cvt_pk_bf16_f32 v153, v144, v145
	v_lshl_add_u64 v[146:147], v[168:169], 0, s[24:25]
	global_store_dwordx4 v[146:147], v[150:153], off
	s_nop 1
	v_lshlrev_b32_e32 v146, 16, v150
	v_and_b32_e32 v147, 0xffff0000, v150
	v_lshlrev_b32_e32 v148, 16, v151
	v_and_b32_e32 v149, 0xffff0000, v151
	v_lshlrev_b32_e32 v150, 16, v152
	v_and_b32_e32 v151, 0xffff0000, v152
	v_lshlrev_b32_e32 v152, 16, v153
	v_and_b32_e32 v153, 0xffff0000, v153
	s_mov_b64 s[28:29], 0

; __device__ __forceinline__ unsigned cvt_pk_bf16(float lo, float hi) { unsigned r; asm volatile("v_cvt_pk_bf16_f32 %0, %1, %2" : "=v"(r) : "v"(lo), "v"(hi)); return r; }
;     __device__ __forceinline__ void operator()(const f32x4 (&acc)[2][2][4][2], const Unit& u, int wr, int wc, int fr, int fq, PG8_LAS float* xt) const {
;     ...
;             for (int m = 0; m < 4; ++m) { const int row = row0 + ai * HALF + m * 16; const size_t off = (size_t)row * 2048 + col0; float s = 0.f;
; #pragma unroll
;                 for (int bj = 0; bj < 2; ++bj) { const size_t o2 = off + bj * HALF;
;                     f32x4 x0 = acc[ai][bj][m][0] * f, x1 = acc[ai][bj][m][1] * f;
;                     if (out_f32) { *(f32x4*)(xout + o2) = x0; *(f32x4*)(xout + o2 + 4) = x1; }
;                     else { u32x4 w; w.x = cvt_pk_bf16(x0[0], x0[1]); w.y = cvt_pk_bf16(x0[2], x0[3]); w.z = cvt_pk_bf16(x1[0], x1[1]); w.w = cvt_pk_bf16(x1[2], x1[3]);
;                         asm volatile("global_store_dwordx4 %0, %1, off sc1\n\ts_nop 1" :: "v"(xb + o2), "v"(w) : "memory");
;                         x0 = (f32x4){__uint_as_float(w.x << 16), __uint_as_float(w.x & 0xffff0000u), __uint_as_float(w.y << 16), __uint_as_float(w.y & 0xffff0000u)};
;                         x1 = (f32x4){__uint_as_float(w.z << 16), __uint_as_float(w.z & 0xffff0000u), __uint_as_float(w.w << 16), __uint_as_float(w.w & 0xffff0000u)}; }
;                     s += (x0[0] * x0[0] + x0[1] * x0[1]) + (x0[2] * x0[2] + x0[3] * x0[3]) + (x1[0] * x1[0] + x1[1] * x1[1]) + (x1[2] * x1[2] + x1[3] * x1[3]); }
.LBB0_883:
	s_or_b64 exec, exec, s[28:29]
	v_or_b32_e32 v130, 32, v166
	s_waitcnt lgkmcnt(0)
	v_ashrrev_i32_e32 v131, 31, v130
	v_lshlrev_b64 v[130:131], 11, v[130:131]
	v_lshl_add_u64 v[146:147], v[130:131], 0, v[164:165]
	v_pk_mul_f32 v[140:141], v[34:35], 0.5 op_sel_hi:[1,0]
	v_pk_mul_f32 v[138:139], v[32:33], 0.5 op_sel_hi:[1,0]
	v_pk_mul_f32 v[144:145], v[38:39], 0.5 op_sel_hi:[1,0]
	v_pk_mul_f32 v[142:143], v[36:37], 0.5 op_sel_hi:[1,0]
	s_mov_b64 s[28:29], -1
	s_and_b64 vcc, exec, s[64:65]
	v_lshl_add_u64 v[168:169], v[146:147], 1, s[44:45]
	s_cbranch_vccz .LBB0_885
	v_cvt_pk_bf16_f32 v134, v138, v139
	v_cvt_pk_bf16_f32 v135, v140, v141
	v_cvt_pk_bf16_f32 v136, v142, v143
	v_cvt_pk_bf16_f32 v137, v144, v145
	s_mov_b64 s[28:29], 0
	global_store_dwordx4 v[168:169], v[134:137], off
	s_nop 1
	v_lshlrev_b32_e32 v130, 16, v134
	v_and_b32_e32 v131, 0xffff0000, v134
	v_lshlrev_b32_e32 v132, 16, v135
	v_and_b32_e32 v133, 0xffff0000, v135
	v_lshlrev_b32_e32 v134, 16, v136
	v_and_b32_e32 v135, 0xffff0000, v136
	v_lshlrev_b32_e32 v136, 16, v137
	v_and_b32_e32 v137, 0xffff0000, v137

; __device__ __forceinline__ unsigned cvt_pk_bf16(float lo, float hi) { unsigned r; asm volatile("v_cvt_pk_bf16_f32 %0, %1, %2" : "=v"(r) : "v"(lo), "v"(hi)); return r; }
;     __device__ __forceinline__ void operator()(const f32x4 (&acc)[2][2][4][2], const Unit& u, int wr, int wc, int fr, int fq, PG8_LAS float* xt) const {
;     ...
;             for (int m = 0; m < 4; ++m) { const int row = row0 + ai * HALF + m * 16; const size_t off = (size_t)row * 2048 + col0; float s = 0.f;
; #pragma unroll
;                 for (int bj = 0; bj < 2; ++bj) { const size_t o2 = off + bj * HALF;
;                     f32x4 x0 = acc[ai][bj][m][0] * f, x1 = acc[ai][bj][m][1] * f;
;                     if (out_f32) { *(f32x4*)(xout + o2) = x0; *(f32x4*)(xout + o2 + 4) = x1; }
;                     else { u32x4 w; w.x = cvt_pk_bf16(x0[0], x0[1]); w.y = cvt_pk_bf16(x0[2], x0[3]); w.z = cvt_pk_bf16(x1[0], x1[1]); w.w = cvt_pk_bf16(x1[2], x1[3]);
;                         asm volatile("global_store_dwordx4 %0, %1, off sc1\n\ts_nop 1" :: "v"(xb + o2), "v"(w) : "memory");
;                         x0 = (f32x4){__uint_as_float(w.x << 16), __uint_as_float(w.x & 0xffff0000u), __uint_as_float(w.y << 16), __uint_as_float(w.y & 0xffff0000u)};
;                         x1 = (f32x4){__uint_as_float(w.z << 16), __uint_as_float(w.z & 0xffff0000u), __uint_as_float(w.w << 16), __uint_as_float(w.w & 0xffff0000u)}; }
;                     s += (x0[0] * x0[0] + x0[1] * x0[1]) + (x0[2] * x0[2] + x0[3] * x0[3]) + (x1[0] * x1[0] + x1[1] * x1[1]) + (x1[2] * x1[2] + x1[3] * x1[3]); }
.LBB0_887:
	s_nop 0
	v_pk_mul_f32 v[140:141], v[42:43], 0.5 op_sel_hi:[1,0]
	v_pk_mul_f32 v[138:139], v[40:41], 0.5 op_sel_hi:[1,0]
	v_pk_mul_f32 v[144:145], v[46:47], 0.5 op_sel_hi:[1,0]
	v_pk_mul_f32 v[142:143], v[44:45], 0.5 op_sel_hi:[1,0]
	s_mov_b64 s[28:29], -1
	s_and_b64 vcc, exec, s[64:65]
	s_cbranch_vccz .LBB0_889
	v_cvt_pk_bf16_f32 v150, v138, v139
	v_cvt_pk_bf16_f32 v151, v140, v141
	v_cvt_pk_bf16_f32 v152, v142, v143
	v_cvt_pk_bf16_f32 v153, v144, v145
	v_lshl_add_u64 v[146:147], v[168:169], 0, s[24:25]
	global_store_dwordx4 v[146:147], v[150:153], off
	s_nop 1
	v_lshlrev_b32_e32 v146, 16, v150
	v_and_b32_e32 v147, 0xffff0000, v150
	v_lshlrev_b32_e32 v148, 16, v151
	v_and_b32_e32 v149, 0xffff0000, v151
	v_lshlrev_b32_e32 v150, 16, v152
	v_and_b32_e32 v151, 0xffff0000, v152
	v_lshlrev_b32_e32 v152, 16, v153
	v_and_b32_e32 v153, 0xffff0000, v153
	s_mov_b64 s[28:29], 0

; __device__ __forceinline__ unsigned cvt_pk_bf16(float lo, float hi) { unsigned r; asm volatile("v_cvt_pk_bf16_f32 %0, %1, %2" : "=v"(r) : "v"(lo), "v"(hi)); return r; }
;     __device__ __forceinline__ void operator()(const f32x4 (&acc)[2][2][4][2], const Unit& u, int wr, int wc, int fr, int fq, PG8_LAS float* xt) const {
;     ...
;             for (int m = 0; m < 4; ++m) { const int row = row0 + ai * HALF + m * 16; const size_t off = (size_t)row * 2048 + col0; float s = 0.f;
; #pragma unroll
;                 for (int bj = 0; bj < 2; ++bj) { const size_t o2 = off + bj * HALF;
;                     f32x4 x0 = acc[ai][bj][m][0] * f, x1 = acc[ai][bj][m][1] * f;
;                     if (out_f32) { *(f32x4*)(xout + o2) = x0; *(f32x4*)(xout + o2 + 4) = x1; }
;                     else { u32x4 w; w.x = cvt_pk_bf16(x0[0], x0[1]); w.y = cvt_pk_bf16(x0[2], x0[3]); w.z = cvt_pk_bf16(x1[0], x1[1]); w.w = cvt_pk_bf16(x1[2], x1[3]);
;                         asm volatile("global_store_dwordx4 %0, %1, off sc1\n\ts_nop 1" :: "v"(xb + o2), "v"(w) : "memory");
;                         x0 = (f32x4){__uint_as_float(w.x << 16), __uint_as_float(w.x & 0xffff0000u), __uint_as_float(w.y << 16), __uint_as_float(w.y & 0xffff0000u)};
;                         x1 = (f32x4){__uint_as_float(w.z << 16), __uint_as_float(w.z & 0xffff0000u), __uint_as_float(w.w << 16), __uint_as_float(w.w & 0xffff0000u)}; }
;                     s += (x0[0] * x0[0] + x0[1] * x0[1]) + (x0[2] * x0[2] + x0[3] * x0[3]) + (x1[0] * x1[0] + x1[1] * x1[1]) + (x1[2] * x1[2] + x1[3] * x1[3]); }
.LBB0_893:
	s_or_b64 exec, exec, s[28:29]
	v_or_b32_e32 v130, 48, v166
	s_waitcnt lgkmcnt(0)
	v_ashrrev_i32_e32 v131, 31, v130
	v_lshlrev_b64 v[130:131], 11, v[130:131]
	v_lshl_add_u64 v[146:147], v[130:131], 0, v[164:165]
	v_pk_mul_f32 v[140:141], v[50:51], 0.5 op_sel_hi:[1,0]
	v_pk_mul_f32 v[138:139], v[48:49], 0.5 op_sel_hi:[1,0]
	v_pk_mul_f32 v[144:145], v[54:55], 0.5 op_sel_hi:[1,0]
	v_pk_mul_f32 v[142:143], v[52:53], 0.5 op_sel_hi:[1,0]
	s_mov_b64 s[28:29], -1
	s_and_b64 vcc, exec, s[64:65]
	v_lshl_add_u64 v[168:169], v[146:147], 1, s[44:45]
	s_cbranch_vccz .LBB0_895
	v_cvt_pk_bf16_f32 v134, v138, v139
	v_cvt_pk_bf16_f32 v135, v140, v141
	v_cvt_pk_bf16_f32 v136, v142, v143
	v_cvt_pk_bf16_f32 v137, v144, v145
	s_mov_b64 s[28:29], 0
	global_store_dwordx4 v[168:169], v[134:137], off
	s_nop 1
	v_lshlrev_b32_e32 v130, 16, v134
	v_and_b32_e32 v131, 0xffff0000, v134
	v_lshlrev_b32_e32 v132, 16, v135
	v_and_b32_e32 v133, 0xffff0000, v135
	v_lshlrev_b32_e32 v134, 16, v136
	v_and_b32_e32 v135, 0xffff0000, v136
	v_lshlrev_b32_e32 v136, 16, v137
	v_and_b32_e32 v137, 0xffff0000, v137

; __device__ __forceinline__ unsigned cvt_pk_bf16(float lo, float hi) { unsigned r; asm volatile("v_cvt_pk_bf16_f32 %0, %1, %2" : "=v"(r) : "v"(lo), "v"(hi)); return r; }
;     __device__ __forceinline__ void operator()(const f32x4 (&acc)[2][2][4][2], const Unit& u, int wr, int wc, int fr, int fq, PG8_LAS float* xt) const {
;     ...
;             for (int m = 0; m < 4; ++m) { const int row = row0 + ai * HALF + m * 16; const size_t off = (size_t)row * 2048 + col0; float s = 0.f;
; #pragma unroll
;                 for (int bj = 0; bj < 2; ++bj) { const size_t o2 = off + bj * HALF;
;                     f32x4 x0 = acc[ai][bj][m][0] * f, x1 = acc[ai][bj][m][1] * f;
;                     if (out_f32) { *(f32x4*)(xout + o2) = x0; *(f32x4*)(xout + o2 + 4) = x1; }
;                     else { u32x4 w; w.x = cvt_pk_bf16(x0[0], x0[1]); w.y = cvt_pk_bf16(x0[2], x0[3]); w.z = cvt_pk_bf16(x1[0], x1[1]); w.w = cvt_pk_bf16(x1[2], x1[3]);
;                         asm volatile("global_store_dwordx4 %0, %1, off sc1\n\ts_nop 1" :: "v"(xb + o2), "v"(w) : "memory");
;                         x0 = (f32x4){__uint_as_float(w.x << 16), __uint_as_float(w.x & 0xffff0000u), __uint_as_float(w.y << 16), __uint_as_float(w.y & 0xffff0000u)};
;                         x1 = (f32x4){__uint_as_float(w.z << 16), __uint_as_float(w.z & 0xffff0000u), __uint_as_float(w.w << 16), __uint_as_float(w.w & 0xffff0000u)}; }
;                     s += (x0[0] * x0[0] + x0[1] * x0[1]) + (x0[2] * x0[2] + x0[3] * x0[3]) + (x1[0] * x1[0] + x1[1] * x1[1]) + (x1[2] * x1[2] + x1[3] * x1[3]); }
.LBB0_897:
	s_nop 0
	v_pk_mul_f32 v[140:141], v[58:59], 0.5 op_sel_hi:[1,0]
	v_pk_mul_f32 v[138:139], v[56:57], 0.5 op_sel_hi:[1,0]
	v_pk_mul_f32 v[144:145], v[62:63], 0.5 op_sel_hi:[1,0]
	v_pk_mul_f32 v[142:143], v[60:61], 0.5 op_sel_hi:[1,0]
	s_mov_b64 s[28:29], -1
	s_and_b64 vcc, exec, s[64:65]
	s_cbranch_vccz .LBB0_899
	v_cvt_pk_bf16_f32 v150, v138, v139
	v_cvt_pk_bf16_f32 v151, v140, v141
	v_cvt_pk_bf16_f32 v152, v142, v143
	v_cvt_pk_bf16_f32 v153, v144, v145
	v_lshl_add_u64 v[146:147], v[168:169], 0, s[24:25]
	global_store_dwordx4 v[146:147], v[150:153], off
	s_nop 1
	v_lshlrev_b32_e32 v146, 16, v150
	v_and_b32_e32 v147, 0xffff0000, v150
	v_lshlrev_b32_e32 v148, 16, v151
	v_and_b32_e32 v149, 0xffff0000, v151
	v_lshlrev_b32_e32 v150, 16, v152
	v_and_b32_e32 v151, 0xffff0000, v152
	v_lshlrev_b32_e32 v152, 16, v153
	v_and_b32_e32 v153, 0xffff0000, v153
	s_mov_b64 s[28:29], 0

; __device__ __forceinline__ unsigned cvt_pk_bf16(float lo, float hi) { unsigned r; asm volatile("v_cvt_pk_bf16_f32 %0, %1, %2" : "=v"(r) : "v"(lo), "v"(hi)); return r; }
;     __device__ __forceinline__ void operator()(const f32x4 (&acc)[2][2][4][2], const Unit& u, int wr, int wc, int fr, int fq, PG8_LAS float* xt) const {
;     ...
;             for (int m = 0; m < 4; ++m) { const int row = row0 + ai * HALF + m * 16; const size_t off = (size_t)row * 2048 + col0; float s = 0.f;
; #pragma unroll
;                 for (int bj = 0; bj < 2; ++bj) { const size_t o2 = off + bj * HALF;
;                     f32x4 x0 = acc[ai][bj][m][0] * f, x1 = acc[ai][bj][m][1] * f;
;                     if (out_f32) { *(f32x4*)(xout + o2) = x0; *(f32x4*)(xout + o2 + 4) = x1; }
;                     else { u32x4 w; w.x = cvt_pk_bf16(x0[0], x0[1]); w.y = cvt_pk_bf16(x0[2], x0[3]); w.z = cvt_pk_bf16(x1[0], x1[1]); w.w = cvt_pk_bf16(x1[2], x1[3]);
;                         asm volatile("global_store_dwordx4 %0, %1, off sc1\n\ts_nop 1" :: "v"(xb + o2), "v"(w) : "memory");
;                         x0 = (f32x4){__uint_as_float(w.x << 16), __uint_as_float(w.x & 0xffff0000u), __uint_as_float(w.y << 16), __uint_as_float(w.y & 0xffff0000u)};
;                         x1 = (f32x4){__uint_as_float(w.z << 16), __uint_as_float(w.z & 0xffff0000u), __uint_as_float(w.w << 16), __uint_as_float(w.w & 0xffff0000u)}; }
;                     s += (x0[0] * x0[0] + x0[1] * x0[1]) + (x0[2] * x0[2] + x0[3] * x0[3]) + (x1[0] * x1[0] + x1[1] * x1[1]) + (x1[2] * x1[2] + x1[3] * x1[3]); }
.LBB0_903:
	s_or_b64 exec, exec, s[28:29]
	s_waitcnt lgkmcnt(0)
	v_lshlrev_b64 v[130:131], 11, v[166:167]
	v_lshl_add_u64 v[130:131], v[130:131], 0, v[164:165]
	s_mov_b64 s[28:29], 0x40000
	v_lshl_add_u64 v[146:147], v[130:131], 0, s[28:29]
	v_pk_mul_f32 v[140:141], v[66:67], 0.5 op_sel_hi:[1,0]
	v_pk_mul_f32 v[138:139], v[64:65], 0.5 op_sel_hi:[1,0]
	v_pk_mul_f32 v[144:145], v[70:71], 0.5 op_sel_hi:[1,0]
	v_pk_mul_f32 v[142:143], v[68:69], 0.5 op_sel_hi:[1,0]
	s_mov_b64 s[28:29], -1
	s_and_b64 vcc, exec, s[64:65]
	v_lshl_add_u64 v[168:169], v[146:147], 1, s[44:45]
	s_cbranch_vccz .LBB0_905
	v_cvt_pk_bf16_f32 v134, v138, v139
	v_cvt_pk_bf16_f32 v135, v140, v141
	v_cvt_pk_bf16_f32 v136, v142, v143
	v_cvt_pk_bf16_f32 v137, v144, v145
	s_mov_b64 s[28:29], 0
	global_store_dwordx4 v[168:169], v[134:137], off
	s_nop 1
	v_lshlrev_b32_e32 v130, 16, v134
	v_and_b32_e32 v131, 0xffff0000, v134
	v_lshlrev_b32_e32 v132, 16, v135
	v_and_b32_e32 v133, 0xffff0000, v135
	v_lshlrev_b32_e32 v134, 16, v136
	v_and_b32_e32 v135, 0xffff0000, v136
	v_lshlrev_b32_e32 v136, 16, v137
	v_and_b32_e32 v137, 0xffff0000, v137

; __device__ __forceinline__ unsigned cvt_pk_bf16(float lo, float hi) { unsigned r; asm volatile("v_cvt_pk_bf16_f32 %0, %1, %2" : "=v"(r) : "v"(lo), "v"(hi)); return r; }
;     __device__ __forceinline__ void operator()(const f32x4 (&acc)[2][2][4][2], const Unit& u, int wr, int wc, int fr, int fq, PG8_LAS float* xt) const {
;     ...
;             for (int m = 0; m < 4; ++m) { const int row = row0 + ai * HALF + m * 16; const size_t off = (size_t)row * 2048 + col0; float s = 0.f;
; #pragma unroll
;                 for (int bj = 0; bj < 2; ++bj) { const size_t o2 = off + bj * HALF;
;                     f32x4 x0 = acc[ai][bj][m][0] * f, x1 = acc[ai][bj][m][1] * f;
;                     if (out_f32) { *(f32x4*)(xout + o2) = x0; *(f32x4*)(xout + o2 + 4) = x1; }
;                     else { u32x4 w; w.x = cvt_pk_bf16(x0[0], x0[1]); w.y = cvt_pk_bf16(x0[2], x0[3]); w.z = cvt_pk_bf16(x1[0], x1[1]); w.w = cvt_pk_bf16(x1[2], x1[3]);
;                         asm volatile("global_store_dwordx4 %0, %1, off sc1\n\ts_nop 1" :: "v"(xb + o2), "v"(w) : "memory");
;                         x0 = (f32x4){__uint_as_float(w.x << 16), __uint_as_float(w.x & 0xffff0000u), __uint_as_float(w.y << 16), __uint_as_float(w.y & 0xffff0000u)};
;                         x1 = (f32x4){__uint_as_float(w.z << 16), __uint_as_float(w.z & 0xffff0000u), __uint_as_float(w.w << 16), __uint_as_float(w.w & 0xffff0000u)}; }
;                     s += (x0[0] * x0[0] + x0[1] * x0[1]) + (x0[2] * x0[2] + x0[3] * x0[3]) + (x1[0] * x1[0] + x1[1] * x1[1]) + (x1[2] * x1[2] + x1[3] * x1[3]); }
.LBB0_907:
	s_nop 0
	v_pk_mul_f32 v[140:141], v[74:75], 0.5 op_sel_hi:[1,0]
	v_pk_mul_f32 v[138:139], v[72:73], 0.5 op_sel_hi:[1,0]
	v_pk_mul_f32 v[144:145], v[78:79], 0.5 op_sel_hi:[1,0]
	v_pk_mul_f32 v[142:143], v[76:77], 0.5 op_sel_hi:[1,0]
	s_mov_b64 s[28:29], -1
	s_and_b64 vcc, exec, s[64:65]
	s_cbranch_vccz .LBB0_909
	v_cvt_pk_bf16_f32 v150, v138, v139
	v_cvt_pk_bf16_f32 v151, v140, v141
	v_cvt_pk_bf16_f32 v152, v142, v143
	v_cvt_pk_bf16_f32 v153, v144, v145
	v_lshl_add_u64 v[146:147], v[168:169], 0, s[24:25]
	global_store_dwordx4 v[146:147], v[150:153], off
	s_nop 1
	v_lshlrev_b32_e32 v146, 16, v150
	v_and_b32_e32 v147, 0xffff0000, v150
	v_lshlrev_b32_e32 v148, 16, v151
	v_and_b32_e32 v149, 0xffff0000, v151
	v_lshlrev_b32_e32 v150, 16, v152
	v_and_b32_e32 v151, 0xffff0000, v152
	v_lshlrev_b32_e32 v152, 16, v153
	v_and_b32_e32 v153, 0xffff0000, v153
	s_mov_b64 s[28:29], 0

; __device__ __forceinline__ unsigned cvt_pk_bf16(float lo, float hi) { unsigned r; asm volatile("v_cvt_pk_bf16_f32 %0, %1, %2" : "=v"(r) : "v"(lo), "v"(hi)); return r; }
;     __device__ __forceinline__ void operator()(const f32x4 (&acc)[2][2][4][2], const Unit& u, int wr, int wc, int fr, int fq, PG8_LAS float* xt) const {
;     ...
;             for (int m = 0; m < 4; ++m) { const int row = row0 + ai * HALF + m * 16; const size_t off = (size_t)row * 2048 + col0; float s = 0.f;
; #pragma unroll
;                 for (int bj = 0; bj < 2; ++bj) { const size_t o2 = off + bj * HALF;
;                     f32x4 x0 = acc[ai][bj][m][0] * f, x1 = acc[ai][bj][m][1] * f;
;                     if (out_f32) { *(f32x4*)(xout + o2) = x0; *(f32x4*)(xout + o2 + 4) = x1; }
;                     else { u32x4 w; w.x = cvt_pk_bf16(x0[0], x0[1]); w.y = cvt_pk_bf16(x0[2], x0[3]); w.z = cvt_pk_bf16(x1[0], x1[1]); w.w = cvt_pk_bf16(x1[2], x1[3]);
;                         asm volatile("global_store_dwordx4 %0, %1, off sc1\n\ts_nop 1" :: "v"(xb + o2), "v"(w) : "memory");
;                         x0 = (f32x4){__uint_as_float(w.x << 16), __uint_as_float(w.x & 0xffff0000u), __uint_as_float(w.y << 16), __uint_as_float(w.y & 0xffff0000u)};
;                         x1 = (f32x4){__uint_as_float(w.z << 16), __uint_as_float(w.z & 0xffff0000u), __uint_as_float(w.w << 16), __uint_as_float(w.w & 0xffff0000u)}; }
;                     s += (x0[0] * x0[0] + x0[1] * x0[1]) + (x0[2] * x0[2] + x0[3] * x0[3]) + (x1[0] * x1[0] + x1[1] * x1[1]) + (x1[2] * x1[2] + x1[3] * x1[3]); }
.LBB0_913:
	s_or_b64 exec, exec, s[28:29]
	s_waitcnt lgkmcnt(0)
	v_lshlrev_b64 v[130:131], 11, v[166:167]
	v_lshl_add_u64 v[130:131], v[130:131], 0, v[164:165]
	s_mov_b64 s[28:29], 0x48000
	v_lshl_add_u64 v[146:147], v[130:131], 0, s[28:29]
	v_pk_mul_f32 v[140:141], v[82:83], 0.5 op_sel_hi:[1,0]
	v_pk_mul_f32 v[138:139], v[80:81], 0.5 op_sel_hi:[1,0]
	v_pk_mul_f32 v[144:145], v[86:87], 0.5 op_sel_hi:[1,0]
	v_pk_mul_f32 v[142:143], v[84:85], 0.5 op_sel_hi:[1,0]
	s_mov_b64 s[28:29], -1
	s_and_b64 vcc, exec, s[64:65]
	v_lshl_add_u64 v[168:169], v[146:147], 1, s[44:45]
	s_cbranch_vccz .LBB0_915
	v_cvt_pk_bf16_f32 v134, v138, v139
	v_cvt_pk_bf16_f32 v135, v140, v141
	v_cvt_pk_bf16_f32 v136, v142, v143
	v_cvt_pk_bf16_f32 v137, v144, v145
	s_mov_b64 s[28:29], 0
	global_store_dwordx4 v[168:169], v[134:137], off
	s_nop 1
	v_lshlrev_b32_e32 v130, 16, v134
	v_and_b32_e32 v131, 0xffff0000, v134
	v_lshlrev_b32_e32 v132, 16, v135
	v_and_b32_e32 v133, 0xffff0000, v135
	v_lshlrev_b32_e32 v134, 16, v136
	v_and_b32_e32 v135, 0xffff0000, v136
	v_lshlrev_b32_e32 v136, 16, v137
	v_and_b32_e32 v137, 0xffff0000, v137

; __device__ __forceinline__ unsigned cvt_pk_bf16(float lo, float hi) { unsigned r; asm volatile("v_cvt_pk_bf16_f32 %0, %1, %2" : "=v"(r) : "v"(lo), "v"(hi)); return r; }
;     __device__ __forceinline__ void operator()(const f32x4 (&acc)[2][2][4][2], const Unit& u, int wr, int wc, int fr, int fq, PG8_LAS float* xt) const {
;     ...
;             for (int m = 0; m < 4; ++m) { const int row = row0 + ai * HALF + m * 16; const size_t off = (size_t)row * 2048 + col0; float s = 0.f;
; #pragma unroll
;                 for (int bj = 0; bj < 2; ++bj) { const size_t o2 = off + bj * HALF;
;                     f32x4 x0 = acc[ai][bj][m][0] * f, x1 = acc[ai][bj][m][1] * f;
;                     if (out_f32) { *(f32x4*)(xout + o2) = x0; *(f32x4*)(xout + o2 + 4) = x1; }
;                     else { u32x4 w; w.x = cvt_pk_bf16(x0[0], x0[1]); w.y = cvt_pk_bf16(x0[2], x0[3]); w.z = cvt_pk_bf16(x1[0], x1[1]); w.w = cvt_pk_bf16(x1[2], x1[3]);
;                         asm volatile("global_store_dwordx4 %0, %1, off sc1\n\ts_nop 1" :: "v"(xb + o2), "v"(w) : "memory");
;                         x0 = (f32x4){__uint_as_float(w.x << 16), __uint_as_float(w.x & 0xffff0000u), __uint_as_float(w.y << 16), __uint_as_float(w.y & 0xffff0000u)};
;                         x1 = (f32x4){__uint_as_float(w.z << 16), __uint_as_float(w.z & 0xffff0000u), __uint_as_float(w.w << 16), __uint_as_float(w.w & 0xffff0000u)}; }
;                     s += (x0[0] * x0[0] + x0[1] * x0[1]) + (x0[2] * x0[2] + x0[3] * x0[3]) + (x1[0] * x1[0] + x1[1] * x1[1]) + (x1[2] * x1[2] + x1[3] * x1[3]); }
.LBB0_917:
	s_nop 0
	v_pk_mul_f32 v[140:141], v[90:91], 0.5 op_sel_hi:[1,0]
	v_pk_mul_f32 v[138:139], v[88:89], 0.5 op_sel_hi:[1,0]
	v_pk_mul_f32 v[144:145], v[94:95], 0.5 op_sel_hi:[1,0]
	v_pk_mul_f32 v[142:143], v[92:93], 0.5 op_sel_hi:[1,0]
	s_mov_b64 s[28:29], -1
	s_and_b64 vcc, exec, s[64:65]
	s_cbranch_vccz .LBB0_919
	v_cvt_pk_bf16_f32 v150, v138, v139
	v_cvt_pk_bf16_f32 v151, v140, v141
	v_cvt_pk_bf16_f32 v152, v142, v143
	v_cvt_pk_bf16_f32 v153, v144, v145
	v_lshl_add_u64 v[146:147], v[168:169], 0, s[24:25]
	global_store_dwordx4 v[146:147], v[150:153], off
	s_nop 1
	v_lshlrev_b32_e32 v146, 16, v150
	v_and_b32_e32 v147, 0xffff0000, v150
	v_lshlrev_b32_e32 v148, 16, v151
	v_and_b32_e32 v149, 0xffff0000, v151
	v_lshlrev_b32_e32 v150, 16, v152
	v_and_b32_e32 v151, 0xffff0000, v152
	v_lshlrev_b32_e32 v152, 16, v153
	v_and_b32_e32 v153, 0xffff0000, v153
	s_mov_b64 s[28:29], 0

; __device__ __forceinline__ unsigned cvt_pk_bf16(float lo, float hi) { unsigned r; asm volatile("v_cvt_pk_bf16_f32 %0, %1, %2" : "=v"(r) : "v"(lo), "v"(hi)); return r; }
;     __device__ __forceinline__ void operator()(const f32x4 (&acc)[2][2][4][2], const Unit& u, int wr, int wc, int fr, int fq, PG8_LAS float* xt) const {
;     ...
;             for (int m = 0; m < 4; ++m) { const int row = row0 + ai * HALF + m * 16; const size_t off = (size_t)row * 2048 + col0; float s = 0.f;
; #pragma unroll
;                 for (int bj = 0; bj < 2; ++bj) { const size_t o2 = off + bj * HALF;
;                     f32x4 x0 = acc[ai][bj][m][0] * f, x1 = acc[ai][bj][m][1] * f;
;                     if (out_f32) { *(f32x4*)(xout + o2) = x0; *(f32x4*)(xout + o2 + 4) = x1; }
;                     else { u32x4 w; w.x = cvt_pk_bf16(x0[0], x0[1]); w.y = cvt_pk_bf16(x0[2], x0[3]); w.z = cvt_pk_bf16(x1[0], x1[1]); w.w = cvt_pk_bf16(x1[2], x1[3]);
;                         asm volatile("global_store_dwordx4 %0, %1, off sc1\n\ts_nop 1" :: "v"(xb + o2), "v"(w) : "memory");
;                         x0 = (f32x4){__uint_as_float(w.x << 16), __uint_as_float(w.x & 0xffff0000u), __uint_as_float(w.y << 16), __uint_as_float(w.y & 0xffff0000u)};
;                         x1 = (f32x4){__uint_as_float(w.z << 16), __uint_as_float(w.z & 0xffff0000u), __uint_as_float(w.w << 16), __uint_as_float(w.w & 0xffff0000u)}; }
;                     s += (x0[0] * x0[0] + x0[1] * x0[1]) + (x0[2] * x0[2] + x0[3] * x0[3]) + (x1[0] * x1[0] + x1[1] * x1[1]) + (x1[2] * x1[2] + x1[3] * x1[3]); }
.LBB0_923:
	s_or_b64 exec, exec, s[28:29]
	s_waitcnt lgkmcnt(0)
	v_lshlrev_b64 v[130:131], 11, v[166:167]
	v_lshl_add_u64 v[130:131], v[130:131], 0, v[164:165]
	s_mov_b64 s[28:29], 0x50000
	v_lshl_add_u64 v[146:147], v[130:131], 0, s[28:29]
	v_pk_mul_f32 v[140:141], v[100:101], 0.5 op_sel_hi:[1,0]
	v_pk_mul_f32 v[138:139], v[98:99], 0.5 op_sel_hi:[1,0]
	v_pk_mul_f32 v[144:145], v[104:105], 0.5 op_sel_hi:[1,0]
	v_pk_mul_f32 v[142:143], v[102:103], 0.5 op_sel_hi:[1,0]
	s_mov_b64 s[28:29], -1
	s_and_b64 vcc, exec, s[64:65]
	v_lshl_add_u64 v[168:169], v[146:147], 1, s[44:45]
	s_cbranch_vccz .LBB0_925
	v_cvt_pk_bf16_f32 v134, v138, v139
	v_cvt_pk_bf16_f32 v135, v140, v141
	v_cvt_pk_bf16_f32 v136, v142, v143
	v_cvt_pk_bf16_f32 v137, v144, v145
	s_mov_b64 s[28:29], 0
	global_store_dwordx4 v[168:169], v[134:137], off
	s_nop 1
	v_lshlrev_b32_e32 v130, 16, v134
	v_and_b32_e32 v131, 0xffff0000, v134
	v_lshlrev_b32_e32 v132, 16, v135
	v_and_b32_e32 v133, 0xffff0000, v135
	v_lshlrev_b32_e32 v134, 16, v136
	v_and_b32_e32 v135, 0xffff0000, v136
	v_lshlrev_b32_e32 v136, 16, v137
	v_and_b32_e32 v137, 0xffff0000, v137

; __device__ __forceinline__ unsigned cvt_pk_bf16(float lo, float hi) { unsigned r; asm volatile("v_cvt_pk_bf16_f32 %0, %1, %2" : "=v"(r) : "v"(lo), "v"(hi)); return r; }
;     __device__ __forceinline__ void operator()(const f32x4 (&acc)[2][2][4][2], const Unit& u, int wr, int wc, int fr, int fq, PG8_LAS float* xt) const {
;     ...
;             for (int m = 0; m < 4; ++m) { const int row = row0 + ai * HALF + m * 16; const size_t off = (size_t)row * 2048 + col0; float s = 0.f;
; #pragma unroll
;                 for (int bj = 0; bj < 2; ++bj) { const size_t o2 = off + bj * HALF;
;                     f32x4 x0 = acc[ai][bj][m][0] * f, x1 = acc[ai][bj][m][1] * f;
;                     if (out_f32) { *(f32x4*)(xout + o2) = x0; *(f32x4*)(xout + o2 + 4) = x1; }
;                     else { u32x4 w; w.x = cvt_pk_bf16(x0[0], x0[1]); w.y = cvt_pk_bf16(x0[2], x0[3]); w.z = cvt_pk_bf16(x1[0], x1[1]); w.w = cvt_pk_bf16(x1[2], x1[3]);
;                         asm volatile("global_store_dwordx4 %0, %1, off sc1\n\ts_nop 1" :: "v"(xb + o2), "v"(w) : "memory");
;                         x0 = (f32x4){__uint_as_float(w.x << 16), __uint_as_float(w.x & 0xffff0000u), __uint_as_float(w.y << 16), __uint_as_float(w.y & 0xffff0000u)};
;                         x1 = (f32x4){__uint_as_float(w.z << 16), __uint_as_float(w.z & 0xffff0000u), __uint_as_float(w.w << 16), __uint_as_float(w.w & 0xffff0000u)}; }
;                     s += (x0[0] * x0[0] + x0[1] * x0[1]) + (x0[2] * x0[2] + x0[3] * x0[3]) + (x1[0] * x1[0] + x1[1] * x1[1]) + (x1[2] * x1[2] + x1[3] * x1[3]); }
.LBB0_927:
	s_nop 0
	v_pk_mul_f32 v[140:141], v[108:109], 0.5 op_sel_hi:[1,0]
	v_pk_mul_f32 v[138:139], v[106:107], 0.5 op_sel_hi:[1,0]
	v_pk_mul_f32 v[144:145], v[112:113], 0.5 op_sel_hi:[1,0]
	v_pk_mul_f32 v[142:143], v[110:111], 0.5 op_sel_hi:[1,0]
	s_mov_b64 s[28:29], -1
	s_and_b64 vcc, exec, s[64:65]
	s_cbranch_vccz .LBB0_929
	v_cvt_pk_bf16_f32 v150, v138, v139
	v_cvt_pk_bf16_f32 v151, v140, v141
	v_cvt_pk_bf16_f32 v152, v142, v143
	v_cvt_pk_bf16_f32 v153, v144, v145
	v_lshl_add_u64 v[146:147], v[168:169], 0, s[24:25]
	global_store_dwordx4 v[146:147], v[150:153], off
	s_nop 1
	v_lshlrev_b32_e32 v146, 16, v150
	v_and_b32_e32 v147, 0xffff0000, v150
	v_lshlrev_b32_e32 v148, 16, v151
	v_and_b32_e32 v149, 0xffff0000, v151
	v_lshlrev_b32_e32 v150, 16, v152
	v_and_b32_e32 v151, 0xffff0000, v152
	v_lshlrev_b32_e32 v152, 16, v153
	v_and_b32_e32 v153, 0xffff0000, v153
	s_mov_b64 s[28:29], 0

; __device__ __forceinline__ unsigned cvt_pk_bf16(float lo, float hi) { unsigned r; asm volatile("v_cvt_pk_bf16_f32 %0, %1, %2" : "=v"(r) : "v"(lo), "v"(hi)); return r; }
;     __device__ __forceinline__ void operator()(const f32x4 (&acc)[2][2][4][2], const Unit& u, int wr, int wc, int fr, int fq, PG8_LAS float* xt) const {
;     ...
;             for (int m = 0; m < 4; ++m) { const int row = row0 + ai * HALF + m * 16; const size_t off = (size_t)row * 2048 + col0; float s = 0.f;
; #pragma unroll
;                 for (int bj = 0; bj < 2; ++bj) { const size_t o2 = off + bj * HALF;
;                     f32x4 x0 = acc[ai][bj][m][0] * f, x1 = acc[ai][bj][m][1] * f;
;                     if (out_f32) { *(f32x4*)(xout + o2) = x0; *(f32x4*)(xout + o2 + 4) = x1; }
;                     else { u32x4 w; w.x = cvt_pk_bf16(x0[0], x0[1]); w.y = cvt_pk_bf16(x0[2], x0[3]); w.z = cvt_pk_bf16(x1[0], x1[1]); w.w = cvt_pk_bf16(x1[2], x1[3]);
;                         asm volatile("global_store_dwordx4 %0, %1, off sc1\n\ts_nop 1" :: "v"(xb + o2), "v"(w) : "memory");
;                         x0 = (f32x4){__uint_as_float(w.x << 16), __uint_as_float(w.x & 0xffff0000u), __uint_as_float(w.y << 16), __uint_as_float(w.y & 0xffff0000u)};
;                         x1 = (f32x4){__uint_as_float(w.z << 16), __uint_as_float(w.z & 0xffff0000u), __uint_as_float(w.w << 16), __uint_as_float(w.w & 0xffff0000u)}; }
;                     s += (x0[0] * x0[0] + x0[1] * x0[1]) + (x0[2] * x0[2] + x0[3] * x0[3]) + (x1[0] * x1[0] + x1[1] * x1[1]) + (x1[2] * x1[2] + x1[3] * x1[3]); }
.LBB0_933:
	s_or_b64 exec, exec, s[28:29]
	s_waitcnt lgkmcnt(0)
	v_lshlrev_b64 v[130:131], 11, v[166:167]
	v_lshl_add_u64 v[130:131], v[130:131], 0, v[164:165]
	s_mov_b64 s[28:29], 0x58000
	v_lshl_add_u64 v[146:147], v[130:131], 0, s[28:29]
	v_pk_mul_f32 v[140:141], v[116:117], 0.5 op_sel_hi:[1,0]
	v_pk_mul_f32 v[138:139], v[114:115], 0.5 op_sel_hi:[1,0]
	v_pk_mul_f32 v[144:145], v[120:121], 0.5 op_sel_hi:[1,0]
	v_pk_mul_f32 v[142:143], v[118:119], 0.5 op_sel_hi:[1,0]
	s_mov_b64 s[28:29], -1
	s_and_b64 vcc, exec, s[64:65]
	v_lshl_add_u64 v[164:165], v[146:147], 1, s[44:45]
	s_cbranch_vccz .LBB0_935
	v_cvt_pk_bf16_f32 v134, v138, v139
	v_cvt_pk_bf16_f32 v135, v140, v141
	v_cvt_pk_bf16_f32 v136, v142, v143
	v_cvt_pk_bf16_f32 v137, v144, v145
	s_mov_b64 s[28:29], 0
	global_store_dwordx4 v[164:165], v[134:137], off
	s_nop 1
	v_lshlrev_b32_e32 v130, 16, v134
	v_and_b32_e32 v131, 0xffff0000, v134
	v_lshlrev_b32_e32 v132, 16, v135
	v_and_b32_e32 v133, 0xffff0000, v135
	v_lshlrev_b32_e32 v134, 16, v136
	v_and_b32_e32 v135, 0xffff0000, v136
	v_lshlrev_b32_e32 v136, 16, v137
	v_and_b32_e32 v137, 0xffff0000, v137

; __device__ __forceinline__ unsigned cvt_pk_bf16(float lo, float hi) { unsigned r; asm volatile("v_cvt_pk_bf16_f32 %0, %1, %2" : "=v"(r) : "v"(lo), "v"(hi)); return r; }
;     __device__ __forceinline__ void operator()(const f32x4 (&acc)[2][2][4][2], const Unit& u, int wr, int wc, int fr, int fq, PG8_LAS float* xt) const {
;     ...
;             for (int m = 0; m < 4; ++m) { const int row = row0 + ai * HALF + m * 16; const size_t off = (size_t)row * 2048 + col0; float s = 0.f;
; #pragma unroll
;                 for (int bj = 0; bj < 2; ++bj) { const size_t o2 = off + bj * HALF;
;                     f32x4 x0 = acc[ai][bj][m][0] * f, x1 = acc[ai][bj][m][1] * f;
;                     if (out_f32) { *(f32x4*)(xout + o2) = x0; *(f32x4*)(xout + o2 + 4) = x1; }
;                     else { u32x4 w; w.x = cvt_pk_bf16(x0[0], x0[1]); w.y = cvt_pk_bf16(x0[2], x0[3]); w.z = cvt_pk_bf16(x1[0], x1[1]); w.w = cvt_pk_bf16(x1[2], x1[3]);
;                         asm volatile("global_store_dwordx4 %0, %1, off sc1\n\ts_nop 1" :: "v"(xb + o2), "v"(w) : "memory");
;                         x0 = (f32x4){__uint_as_float(w.x << 16), __uint_as_float(w.x & 0xffff0000u), __uint_as_float(w.y << 16), __uint_as_float(w.y & 0xffff0000u)};
;                         x1 = (f32x4){__uint_as_float(w.z << 16), __uint_as_float(w.z & 0xffff0000u), __uint_as_float(w.w << 16), __uint_as_float(w.w & 0xffff0000u)}; }
;                     s += (x0[0] * x0[0] + x0[1] * x0[1]) + (x0[2] * x0[2] + x0[3] * x0[3]) + (x1[0] * x1[0] + x1[1] * x1[1]) + (x1[2] * x1[2] + x1[3] * x1[3]); }
.LBB0_937:
	s_nop 0
	v_pk_mul_f32 v[140:141], v[124:125], 0.5 op_sel_hi:[1,0]
	v_pk_mul_f32 v[138:139], v[122:123], 0.5 op_sel_hi:[1,0]
	v_pk_mul_f32 v[144:145], v[128:129], 0.5 op_sel_hi:[1,0]
	v_pk_mul_f32 v[142:143], v[126:127], 0.5 op_sel_hi:[1,0]
	s_mov_b64 s[28:29], -1
	s_and_b64 vcc, exec, s[64:65]
	s_cbranch_vccz .LBB0_939
	v_cvt_pk_bf16_f32 v150, v138, v139
	v_cvt_pk_bf16_f32 v151, v140, v141
	v_cvt_pk_bf16_f32 v152, v142, v143
	v_cvt_pk_bf16_f32 v153, v144, v145
	v_lshl_add_u64 v[146:147], v[164:165], 0, s[24:25]
	global_store_dwordx4 v[146:147], v[150:153], off
	s_nop 1
	v_lshlrev_b32_e32 v146, 16, v150
	v_and_b32_e32 v147, 0xffff0000, v150
	v_lshlrev_b32_e32 v148, 16, v151
	v_and_b32_e32 v149, 0xffff0000, v151
	v_lshlrev_b32_e32 v150, 16, v152
	v_and_b32_e32 v151, 0xffff0000, v152
	v_lshlrev_b32_e32 v152, 16, v153
	v_and_b32_e32 v153, 0xffff0000, v153
	s_mov_b64 s[28:29], 0
